# W_out projection epilogue: bf16 residual-stream stores marked nt (non-temporal)
# baseline (speedup 1.0000x reference)
;     __device__ __forceinline__ void operator()(Acc& acc, const Unit& u, int wr, int wc, int fr, int fq, LAS unsigned char* lds) const {
;         const int col0 = u.pn * BM + wc * 32 + 4 * fq;
;         if (STp) row_stats_table(lds, STp, u.pm);
;         const LAS f32x2* SL = (const LAS f32x2*)(lds + SL_OFF);
;         f32x4 gg[2][2], bb[2][2];
;         if (STp) {
; #pragma unroll
;             for (int bj = 0; bj < 2; ++bj)
; #pragma unroll
;                 for (int n = 0; n < 2; ++n) { gg[bj][n] = *(const GASP f32x4*)(gam + col0 + bj * HALF + n * 16); bb[bj][n] = *(const GASP f32x4*)(bet + col0 + bj * HALF + n * 16); }
;         }
; #pragma unroll
;         for (int ai = 0; ai < 2; ++ai)
; #pragma unroll
;             for (int m = 0; m < 4; ++m) {
;                 const int rl = ai * HALF + wr * 64 + m * 16 + fr, row = u.pm * BM + rl;
;                 const float* rp = (row < split) ? res0 + (size_t)row * D : res1 + (size_t)(row - split) * D;
;                 float* op = out + (size_t)row * D;
;                 f32x2 st = (f32x2){0.f, 1.f}; if (STp) st = SL[rl];
;                 float s = 0.f, q = 0.f;
; #pragma unroll
;                 for (int bj = 0; bj < 2; ++bj)
; #pragma unroll
;                     for (int n = 0; n < 2; ++n) { const int c = col0 + bj * HALF + n * 16; f32x4 r;
;                         if (resb) { const u32x2 w = *(const GASP u32x2*)(resb + (size_t)row * D + c);
;                             r = (f32x4){__uint_as_float(w.x << 16), __uint_as_float(w.x & 0xffff0000u), __uint_as_float(w.y << 16), __uint_as_float(w.y & 0xffff0000u)}; }
;                         else r = *(const GASP f32x4*)(rp + c);
;                         if (STp) r = (r - st[0]) * st[1] * gg[bj][n] + bb[bj][n];
;                         const f32x4 o = r * ALPHA + acc[ai][bj][m][n] * scale;
;                         if (out) *(GASP f32x4*)(op + c) = o;
;                         if (ob) { u32x2 w; w.x = pk2(o[0], o[1]); w.y = pk2(o[2], o[3]); *(GASP u32x2*)(ob + (size_t)row * D + c) = w; }
;                         s += (o[0] + o[1]) + (o[2] + o[3]); q += (o[0] * o[0] + o[1] * o[1]) + (o[2] * o[2] + o[3] * o[3]); }
;                 if (STn) { s += __shfl_xor(s, 16); s += __shfl_xor(s, 32); q += __shfl_xor(q, 16); q += __shfl_xor(q, 32);
;                     if (fq == 0) *(GASP f32x2*)(STn + (size_t)row * 32 + (u.pn * 4 + wc) * 2) = (f32x2){s, q}; }
.LBB0_1044:
	s_or_b64 exec, exec, s[60:61]
	v_add_u32_e32 v176, s37, v180
	v_ashrrev_i32_e32 v64, 31, v176
	v_cmp_gt_i32_e32 vcc, s73, v176
	v_lshl_or_b32 v174, s50, 8, v182
	v_ashrrev_i32_e32 v175, 31, v174
	v_cndmask_b32_e32 v177, 0, v64, vcc
	v_lshlrev_b64 v[64:65], 11, v[176:177]
	v_lshl_add_u64 v[64:65], s[42:43], 0, v[64:65]
	s_waitcnt lgkmcnt(0)
	s_barrier
	v_lshl_add_u64 v[178:179], v[174:175], 1, v[64:65]
	global_load_dwordx2 v[204:205], v[178:179], off
	global_load_dwordx2 v[206:207], v[178:179], off offset:32
	global_load_dwordx2 v[210:211], v[178:179], off offset:256
	v_lshlrev_b64 v[64:65], 2, v[174:175]
	v_lshl_add_u64 v[92:93], s[18:19], 0, v[64:65]
	v_lshl_add_u64 v[88:89], s[16:17], 0, v[64:65]
	global_load_dwordx4 v[64:67], v[92:93], off
	global_load_dwordx4 v[76:79], v[88:89], off
	global_load_dwordx4 v[68:71], v[88:89], off offset:64
	global_load_dwordx4 v[80:83], v[92:93], off offset:64
	global_load_dwordx4 v[72:75], v[88:89], off offset:512
	global_load_dwordx4 v[84:87], v[92:93], off offset:512
	global_load_dwordx2 v[212:213], v[178:179], off offset:288
	ds_read_b64 v[214:215], v184
	global_load_dwordx4 v[88:91], v[88:89], off offset:576
	s_nop 0
	global_load_dwordx4 v[92:95], v[92:93], off offset:576
	s_lshl_b32 s14, s50, 3
	s_or_b32 s14, s14, s69
	s_ashr_i32 s15, s14, 31
	v_add_u32_e32 v242, s37, v185
	v_mov_b32_e32 v243, 0
	v_lshlrev_b64 v[242:243], 11, v[242:243]
	v_lshl_add_u64 v[242:243], s[42:43], 0, v[242:243]
	v_lshl_add_u64 v[242:243], v[174:175], 1, v[242:243]
	global_load_dwordx2 v[236:237], v[242:243], off
	global_load_dwordx2 v[238:239], v[242:243], off offset:32
	global_load_dwordx2 v[240:241], v[242:243], off offset:256
	global_load_dwordx2 v[242:243], v[242:243], off offset:288
	v_add_u32_e32 v250, s37, v187
	v_mov_b32_e32 v251, 0
	v_lshlrev_b64 v[250:251], 11, v[250:251]
	v_lshl_add_u64 v[250:251], s[42:43], 0, v[250:251]
	v_lshl_add_u64 v[250:251], v[174:175], 1, v[250:251]
	global_load_dwordx2 v[244:245], v[250:251], off
	global_load_dwordx2 v[246:247], v[250:251], off offset:32
	global_load_dwordx2 v[248:249], v[250:251], off offset:256
	global_load_dwordx2 v[250:251], v[250:251], off offset:288
	s_waitcnt vmcnt(8)
	v_lshlrev_b32_e32 v165, 16, v204
	v_and_b32_e32 v204, 0xffff0000, v204
	v_lshlrev_b32_e32 v216, 16, v205
	v_and_b32_e32 v217, 0xffff0000, v205
	v_lshlrev_b32_e32 v222, 16, v206
	v_and_b32_e32 v223, 0xffff0000, v206
	v_lshlrev_b32_e32 v224, 16, v207
	v_and_b32_e32 v225, 0xffff0000, v207
	v_lshlrev_b32_e32 v226, 16, v210
	v_and_b32_e32 v227, 0xffff0000, v210
	v_lshlrev_b32_e32 v228, 16, v211
	v_and_b32_e32 v229, 0xffff0000, v211
	s_waitcnt lgkmcnt(0)
	v_sub_f32_e32 v205, v204, v214
	v_sub_f32_e32 v204, v165, v214
	v_sub_f32_e32 v207, v217, v214
	v_sub_f32_e32 v206, v216, v214
	v_sub_f32_e32 v211, v225, v214
	v_sub_f32_e32 v210, v224, v214
	v_sub_f32_e32 v217, v223, v214
	v_sub_f32_e32 v216, v222, v214
	v_pk_mul_f32 v[206:207], v[214:215], v[206:207] op_sel:[1,0]
	v_pk_mul_f32 v[204:205], v[214:215], v[204:205] op_sel:[1,0]
	v_pk_mul_f32 v[216:217], v[214:215], v[216:217] op_sel:[1,0]
	v_pk_mul_f32 v[210:211], v[214:215], v[210:211] op_sel:[1,0]
	v_sub_f32_e32 v219, v229, v214
	v_sub_f32_e32 v218, v228, v214
	v_sub_f32_e32 v221, v227, v214
	v_sub_f32_e32 v220, v226, v214
	v_pk_fma_f32 v[204:205], v[76:77], v[204:205], v[64:65]
	v_pk_fma_f32 v[206:207], v[78:79], v[206:207], v[66:67]
	v_pk_fma_f32 v[210:211], v[70:71], v[210:211], v[82:83]
	v_pk_fma_f32 v[216:217], v[68:69], v[216:217], v[80:81]
	v_pk_mul_f32 v[220:221], v[214:215], v[220:221] op_sel:[1,0]
	v_pk_mul_f32 v[218:219], v[214:215], v[218:219] op_sel:[1,0]
	v_pk_fma_f32 v[158:159], v[206:207], s[34:35], v[158:159] op_sel_hi:[1,0,1]
	v_pk_fma_f32 v[156:157], v[204:205], s[34:35], v[156:157] op_sel_hi:[1,0,1]
	v_cndmask_b32_e64 v205, v217, v223, s[10:11]
	v_cndmask_b32_e64 v204, v216, v222, s[10:11]
	v_cndmask_b32_e64 v207, v211, v225, s[10:11]
	v_cndmask_b32_e64 v206, v210, v224, s[10:11]
	v_pk_fma_f32 v[218:219], v[74:75], v[218:219], v[86:87]
	v_pk_fma_f32 v[220:221], v[72:73], v[220:221], v[84:85]
	v_pk_fma_f32 v[154:155], v[206:207], s[34:35], v[154:155] op_sel_hi:[1,0,1]
	v_pk_fma_f32 v[152:153], v[204:205], s[34:35], v[152:153] op_sel_hi:[1,0,1]
	v_cndmask_b32_e64 v210, v220, v226, s[10:11]
	v_cndmask_b32_e64 v217, v219, v229, s[10:11]
	v_cvt_pk_bf16_f32 v220, v156, v157
	v_add_f32_e32 v222, v156, v157
	v_mul_f32_e32 v219, v156, v156
	v_mul_f32_e32 v157, v157, v157
	v_cvt_pk_bf16_f32 v204, v152, v153
	v_cvt_pk_bf16_f32 v205, v154, v155
	v_mul_f32_e32 v156, v154, v154
	global_store_dwordx2 v[178:179], v[204:205], off offset:32 nt
	v_pk_fma_f32 v[204:205], v[154:155], v[154:155], v[156:157] op_sel_hi:[1,1,0]
	v_cndmask_b32_e64 v211, v221, v227, s[10:11]
	v_lshlrev_b32_e32 v165, 16, v213
	v_and_b32_e32 v204, 0xffff0000, v213
	v_cvt_pk_bf16_f32 v221, v158, v159
	v_add_f32_e32 v224, v158, v159
	v_mul_f32_e32 v227, v158, v158
	v_pk_fma_f32 v[206:207], v[210:211], s[34:35], v[148:149] op_sel_hi:[1,0,1]
	v_lshlrev_b32_e32 v156, 16, v212
	v_and_b32_e32 v158, 0xffff0000, v212
	v_sub_f32_e32 v149, v204, v214
	v_sub_f32_e32 v148, v165, v214
	v_sub_f32_e32 v213, v158, v214
	v_sub_f32_e32 v212, v156, v214
	v_pk_mul_f32 v[148:149], v[214:215], v[148:149] op_sel:[1,0]
	v_pk_mul_f32 v[212:213], v[214:215], v[212:213] op_sel:[1,0]
	v_pk_fma_f32 v[148:149], v[90:91], v[148:149], v[94:95]
	v_pk_fma_f32 v[212:213], v[88:89], v[212:213], v[92:93]
	v_cndmask_b32_e64 v149, v149, v204, s[10:11]
	v_cndmask_b32_e64 v148, v148, v165, s[10:11]
	v_mul_f32_e32 v159, v159, v159
	v_cndmask_b32_e64 v216, v218, v228, s[10:11]
	v_cndmask_b32_e64 v213, v213, v158, s[10:11]
; #define GASP __attribute__((address_space(1)))
;     __device__ __forceinline__ void operator()(Acc& acc, const Unit& u, int wr, int wc, int fr, int fq, LAS unsigned char* lds) const {
;     ...
;                 const int rl = ai * HALF + wr * 64 + m * 16 + fr, row = u.pm * BM + rl;
;                 const float* rp = (row < split) ? res0 + (size_t)row * D : res1 + (size_t)(row - split) * D;
;                 float* op = out + (size_t)row * D;
;                 f32x2 st = (f32x2){0.f, 1.f}; if (STp) st = SL[rl];
;                 float s = 0.f, q = 0.f;
; #pragma unroll
;                 for (int bj = 0; bj < 2; ++bj)
; #pragma unroll
;                     for (int n = 0; n < 2; ++n) { const int c = col0 + bj * HALF + n * 16; f32x4 r;
;                         if (resb) { const u32x2 w = *(const GASP u32x2*)(resb + (size_t)row * D + c);
;                             r = (f32x4){__uint_as_float(w.x << 16), __uint_as_float(w.x & 0xffff0000u), __uint_as_float(w.y << 16), __uint_as_float(w.y & 0xffff0000u)}; }
;                         else r = *(const GASP f32x4*)(rp + c);
;                         if (STp) r = (r - st[0]) * st[1] * gg[bj][n] + bb[bj][n];
;                         const f32x4 o = r * ALPHA + acc[ai][bj][m][n] * scale;
;                         if (out) *(GASP f32x4*)(op + c) = o;
;                         if (ob) { u32x2 w; w.x = pk2(o[0], o[1]); w.y = pk2(o[2], o[3]); *(GASP u32x2*)(ob + (size_t)row * D + c) = w; }
;                         s += (o[0] + o[1]) + (o[2] + o[3]); q += (o[0] * o[0] + o[1] * o[1]) + (o[2] * o[2] + o[3] * o[3]); }
;                 if (STn) { s += __shfl_xor(s, 16); s += __shfl_xor(s, 32); q += __shfl_xor(q, 16); q += __shfl_xor(q, 32);
;                     if (fq == 0) *(GASP f32x2*)(STn + (size_t)row * 32 + (u.pn * 4 + wc) * 2) = (f32x2){s, q}; }
	v_cndmask_b32_e64 v212, v212, v156, s[10:11]
	v_pk_fma_f32 v[214:215], v[148:149], s[34:35], v[146:147] op_sel_hi:[1,0,1]
	v_and_b32_e32 v146, 64, v203
	v_mov_b32_e32 v218, v152
	v_mov_b32_e32 v156, v153
	v_mov_b32_e32 v226, v154
	v_mov_b32_e32 v158, v155
	v_mul_f32_e32 v223, v152, v152
	v_mul_f32_e32 v225, v153, v153
	v_pk_fma_f32 v[212:213], v[212:213], s[34:35], v[144:145] op_sel_hi:[1,0,1]
	v_xor_b32_e32 v144, 16, v203
	v_add_u32_e32 v149, 64, v146
	v_pk_add_f32 v[152:153], v[218:219], v[156:157]
	v_pk_add_f32 v[154:155], v[226:227], v[158:159]
	v_pk_fma_f32 v[150:151], v[216:217], s[34:35], v[150:151] op_sel_hi:[1,0,1]
	v_cmp_lt_i32_e32 vcc, v144, v149
	v_pk_add_f32 v[152:153], v[152:153], v[154:155]
	v_pk_add_f32 v[154:155], v[222:223], v[224:225]
	v_mov_b32_e32 v165, v205
	global_store_dwordx2 v[178:179], v[220:221], off nt
	v_mul_f32_e32 v217, v206, v206
	v_mul_f32_e32 v221, v207, v207
	v_mul_f32_e32 v229, v150, v150
	v_mul_f32_e32 v231, v151, v151
	v_cndmask_b32_e32 v144, v203, v144, vcc
	v_pk_add_f32 v[154:155], v[154:155], v[164:165]
	v_mov_b32_e32 v216, v206
	v_mov_b32_e32 v220, v207
	v_mov_b32_e32 v228, v150
	v_mov_b32_e32 v230, v151
	v_cvt_pk_bf16_f32 v211, v150, v151
	v_mul_f32_e32 v145, v212, v212
	v_mul_f32_e32 v147, v213, v213
	v_mul_f32_e32 v233, v214, v214
	v_mul_f32_e32 v235, v215, v215
	v_lshlrev_b32_e32 v148, 2, v144
	v_pk_add_f32 v[152:153], v[152:153], v[154:155]
	v_pk_add_f32 v[154:155], v[216:217], v[220:221]
	v_pk_add_f32 v[150:151], v[228:229], v[230:231]
	v_mov_b32_e32 v144, v212
	v_mov_b32_e32 v146, v213
	v_mov_b32_e32 v232, v214
	v_mov_b32_e32 v234, v215
	v_pk_add_f32 v[150:151], v[154:155], v[150:151]
	v_pk_add_f32 v[144:145], v[144:145], v[146:147]
	v_pk_add_f32 v[146:147], v[232:233], v[234:235]
	v_pk_add_f32 v[150:151], v[152:153], v[150:151]
	v_pk_add_f32 v[144:145], v[144:145], v[146:147]
	v_cvt_pk_bf16_f32 v210, v206, v207
	v_pk_add_f32 v[144:145], v[150:151], v[144:145]
	ds_bpermute_b32 v146, v148, v144
	ds_bpermute_b32 v147, v148, v145
	v_xor_b32_e32 v150, 32, v203
	v_cmp_lt_i32_e32 vcc, v150, v149
	v_cvt_pk_bf16_f32 v151, v214, v215
	global_store_dwordx2 v[178:179], v[210:211], off offset:256 nt
	v_cndmask_b32_e32 v149, v203, v150, vcc
	v_lshlrev_b32_e32 v149, 2, v149
	s_waitcnt lgkmcnt(0)
	v_pk_add_f32 v[144:145], v[144:145], v[146:147]
	ds_bpermute_b32 v146, v149, v144
	ds_bpermute_b32 v147, v149, v145
	v_cvt_pk_bf16_f32 v150, v212, v213
	global_store_dwordx2 v[178:179], v[150:151], off offset:288 nt
	s_and_saveexec_b64 s[50:51], s[8:9]
	s_cbranch_execz .LBB0_1046
	s_waitcnt lgkmcnt(0)
	v_pk_add_f32 v[144:145], v[144:145], v[146:147]
	v_lshlrev_b64 v[146:147], 7, v[176:177]
	v_lshl_add_u64 v[146:147], s[24:25], 0, v[146:147]
	v_lshl_add_u64 v[146:147], s[14:15], 2, v[146:147]
	global_store_dwordx2 v[146:147], v[144:145], off
.LBB0_1046:
	s_or_b64 exec, exec, s[50:51]
	v_add_u32_e32 v144, s37, v185
	v_ashrrev_i32_e32 v145, 31, v144
	v_cmp_gt_i32_e32 vcc, s73, v144
	s_nop 1
	v_cndmask_b32_e32 v145, 0, v145, vcc
	s_waitcnt lgkmcnt(0)
	v_lshlrev_b64 v[146:147], 11, v[144:145]
	v_lshl_add_u64 v[146:147], s[42:43], 0, v[146:147]
	v_lshl_add_u64 v[146:147], v[174:175], 1, v[146:147]
	ds_read_b64 v[158:159], v186
	s_waitcnt vmcnt(9)
	v_lshlrev_b32_e32 v176, 16, v237
	v_and_b32_e32 v177, 0xffff0000, v237
	v_lshlrev_b32_e32 v212, 16, v239
	v_and_b32_e32 v213, 0xffff0000, v239
	v_lshlrev_b32_e32 v165, 16, v236
	v_and_b32_e32 v150, 0xffff0000, v236
	v_lshlrev_b32_e32 v210, 16, v238
	v_and_b32_e32 v211, 0xffff0000, v238
	v_lshlrev_b32_e32 v214, 16, v240
	v_and_b32_e32 v215, 0xffff0000, v240
	v_lshlrev_b32_e32 v216, 16, v241
	v_and_b32_e32 v217, 0xffff0000, v241
	s_waitcnt lgkmcnt(0)
	v_sub_f32_e32 v153, v177, v158
	v_sub_f32_e32 v152, v176, v158
	v_sub_f32_e32 v155, v213, v158
	v_sub_f32_e32 v154, v212, v158
	v_lshlrev_b32_e32 v218, 16, v242
	v_and_b32_e32 v219, 0xffff0000, v242
	v_lshlrev_b32_e32 v220, 16, v243
	v_and_b32_e32 v221, 0xffff0000, v243
	v_add_u32_e32 v242, s37, v189
	v_mov_b32_e32 v243, 0
	v_lshlrev_b64 v[242:243], 11, v[242:243]
	v_lshl_add_u64 v[242:243], s[42:43], 0, v[242:243]
	v_lshl_add_u64 v[242:243], v[174:175], 1, v[242:243]
	global_load_dwordx2 v[236:237], v[242:243], off
	global_load_dwordx2 v[238:239], v[242:243], off offset:32
	global_load_dwordx2 v[240:241], v[242:243], off offset:256
	global_load_dwordx2 v[242:243], v[242:243], off offset:288
	v_sub_f32_e32 v151, v150, v158
	v_sub_f32_e32 v150, v165, v158
	v_sub_f32_e32 v157, v211, v158
	v_sub_f32_e32 v156, v210, v158
	v_pk_mul_f32 v[152:153], v[158:159], v[152:153] op_sel:[1,0]
	v_pk_mul_f32 v[154:155], v[158:159], v[154:155] op_sel:[1,0]
	v_sub_f32_e32 v177, v217, v158
	v_sub_f32_e32 v176, v216, v158
	v_sub_f32_e32 v179, v215, v158
	v_sub_f32_e32 v178, v214, v158
	v_sub_f32_e32 v207, v219, v158
	v_sub_f32_e32 v206, v218, v158
	v_pk_mul_f32 v[150:151], v[158:159], v[150:151] op_sel:[1,0]
	v_pk_mul_f32 v[156:157], v[158:159], v[156:157] op_sel:[1,0]
	v_pk_fma_f32 v[152:153], v[78:79], v[152:153], v[66:67]
	v_pk_fma_f32 v[154:155], v[70:71], v[154:155], v[82:83]
	v_sub_f32_e32 v205, v221, v158
	v_sub_f32_e32 v204, v220, v158
	v_pk_mul_f32 v[178:179], v[158:159], v[178:179] op_sel:[1,0]
	v_pk_mul_f32 v[176:177], v[158:159], v[176:177] op_sel:[1,0]
	v_pk_mul_f32 v[206:207], v[158:159], v[206:207] op_sel:[1,0]
	v_pk_fma_f32 v[150:151], v[76:77], v[150:151], v[64:65]
	v_pk_fma_f32 v[156:157], v[68:69], v[156:157], v[80:81]
	v_pk_fma_f32 v[142:143], v[152:153], s[34:35], v[142:143] op_sel_hi:[1,0,1]
	v_cndmask_b32_e64 v153, v155, v213, s[10:11]
	v_cndmask_b32_e64 v152, v154, v212, s[10:11]
	v_pk_mul_f32 v[158:159], v[158:159], v[204:205] op_sel:[1,0]
; #define GASP __attribute__((address_space(1)))
;     __device__ __forceinline__ void operator()(Acc& acc, const Unit& u, int wr, int wc, int fr, int fq, LAS unsigned char* lds) const {
;     ...
;                 const int rl = ai * HALF + wr * 64 + m * 16 + fr, row = u.pm * BM + rl;
;                 const float* rp = (row < split) ? res0 + (size_t)row * D : res1 + (size_t)(row - split) * D;
;                 float* op = out + (size_t)row * D;
;                 f32x2 st = (f32x2){0.f, 1.f}; if (STp) st = SL[rl];
;                 float s = 0.f, q = 0.f;
; #pragma unroll
;                 for (int bj = 0; bj < 2; ++bj)
; #pragma unroll
;                     for (int n = 0; n < 2; ++n) { const int c = col0 + bj * HALF + n * 16; f32x4 r;
;                         if (resb) { const u32x2 w = *(const GASP u32x2*)(resb + (size_t)row * D + c);
;                             r = (f32x4){__uint_as_float(w.x << 16), __uint_as_float(w.x & 0xffff0000u), __uint_as_float(w.y << 16), __uint_as_float(w.y & 0xffff0000u)}; }
;                         else r = *(const GASP f32x4*)(rp + c);
;                         if (STp) r = (r - st[0]) * st[1] * gg[bj][n] + bb[bj][n];
;                         const f32x4 o = r * ALPHA + acc[ai][bj][m][n] * scale;
;                         if (out) *(GASP f32x4*)(op + c) = o;
;                         if (ob) { u32x2 w; w.x = pk2(o[0], o[1]); w.y = pk2(o[2], o[3]); *(GASP u32x2*)(ob + (size_t)row * D + c) = w; }
;                         s += (o[0] + o[1]) + (o[2] + o[3]); q += (o[0] * o[0] + o[1] * o[1]) + (o[2] * o[2] + o[3] * o[3]); }
;                 if (STn) { s += __shfl_xor(s, 16); s += __shfl_xor(s, 32); q += __shfl_xor(q, 16); q += __shfl_xor(q, 32);
;                     if (fq == 0) *(GASP f32x2*)(STn + (size_t)row * 32 + (u.pn * 4 + wc) * 2) = (f32x2){s, q}; }
	v_pk_fma_f32 v[176:177], v[74:75], v[176:177], v[86:87]
	v_pk_fma_f32 v[178:179], v[72:73], v[178:179], v[84:85]
	v_pk_fma_f32 v[204:205], v[88:89], v[206:207], v[92:93]
	v_pk_fma_f32 v[140:141], v[150:151], s[34:35], v[140:141] op_sel_hi:[1,0,1]
	v_cndmask_b32_e64 v151, v157, v211, s[10:11]
	v_cndmask_b32_e64 v150, v156, v210, s[10:11]
	v_pk_fma_f32 v[138:139], v[152:153], s[34:35], v[138:139] op_sel_hi:[1,0,1]
	v_cndmask_b32_e64 v154, v178, v214, s[10:11]
	v_cndmask_b32_e64 v156, v176, v216, s[10:11]
	v_cndmask_b32_e64 v176, v204, v218, s[10:11]
	v_cvt_pk_bf16_f32 v178, v140, v141
	v_add_f32_e32 v204, v140, v141
	v_mul_f32_e32 v211, v140, v140
	v_mul_f32_e32 v141, v141, v141
	v_pk_fma_f32 v[136:137], v[150:151], s[34:35], v[136:137] op_sel_hi:[1,0,1]
	v_mul_f32_e32 v140, v138, v138
	v_cndmask_b32_e64 v155, v179, v215, s[10:11]
	v_cvt_pk_bf16_f32 v179, v142, v143
	v_add_f32_e32 v206, v142, v143
	v_mul_f32_e32 v213, v142, v142
	v_mul_f32_e32 v143, v143, v143
	v_pk_fma_f32 v[214:215], v[138:139], v[138:139], v[140:141] op_sel_hi:[1,1,0]
	v_mov_b32_e32 v210, v136
	v_mov_b32_e32 v140, v137
	v_mov_b32_e32 v212, v138
	v_mov_b32_e32 v142, v139
	v_pk_fma_f32 v[158:159], v[90:91], v[158:159], v[94:95]
	v_cndmask_b32_e64 v157, v177, v217, s[10:11]
	v_cndmask_b32_e64 v177, v205, v219, s[10:11]
	v_cvt_pk_bf16_f32 v150, v136, v137
	v_mul_f32_e32 v205, v136, v136
	v_mul_f32_e32 v207, v137, v137
	v_pk_add_f32 v[136:137], v[210:211], v[140:141]
	v_pk_add_f32 v[140:141], v[212:213], v[142:143]
	v_pk_fma_f32 v[134:135], v[156:157], s[34:35], v[134:135] op_sel_hi:[1,0,1]
	v_pk_fma_f32 v[132:133], v[154:155], s[34:35], v[132:133] op_sel_hi:[1,0,1]
	v_cndmask_b32_e64 v159, v159, v221, s[10:11]
	v_cndmask_b32_e64 v158, v158, v220, s[10:11]
	v_pk_add_f32 v[136:137], v[136:137], v[140:141]
	v_pk_add_f32 v[140:141], v[204:205], v[206:207]
	v_mov_b32_e32 v165, v215
	global_store_dwordx2 v[146:147], v[178:179], off nt
	v_mul_f32_e32 v153, v132, v132
	v_mul_f32_e32 v155, v133, v133
	v_mul_f32_e32 v157, v134, v134
	v_mul_f32_e32 v179, v135, v135
	v_pk_fma_f32 v[158:159], v[158:159], s[34:35], v[130:131] op_sel_hi:[1,0,1]
	v_pk_fma_f32 v[176:177], v[176:177], s[34:35], v[128:129] op_sel_hi:[1,0,1]
	v_pk_add_f32 v[140:141], v[140:141], v[164:165]
	v_mov_b32_e32 v152, v132
	v_mov_b32_e32 v154, v133
	v_mov_b32_e32 v156, v134
	v_mov_b32_e32 v178, v135
	v_mul_f32_e32 v129, v176, v176
	v_mul_f32_e32 v131, v177, v177
	v_mul_f32_e32 v217, v158, v158
	v_mul_f32_e32 v219, v159, v159
	v_pk_add_f32 v[136:137], v[136:137], v[140:141]
	v_pk_add_f32 v[140:141], v[152:153], v[154:155]
	v_pk_add_f32 v[142:143], v[156:157], v[178:179]
	v_mov_b32_e32 v128, v176
	v_mov_b32_e32 v130, v177
	v_mov_b32_e32 v216, v158
	v_mov_b32_e32 v218, v159
	v_pk_add_f32 v[140:141], v[140:141], v[142:143]
	v_pk_add_f32 v[128:129], v[128:129], v[130:131]
	v_pk_add_f32 v[130:131], v[216:217], v[218:219]
	v_pk_add_f32 v[136:137], v[136:137], v[140:141]
	v_pk_add_f32 v[128:129], v[128:129], v[130:131]
	v_cvt_pk_bf16_f32 v132, v132, v133
	v_pk_add_f32 v[128:129], v[136:137], v[128:129]
	ds_bpermute_b32 v130, v148, v128
	ds_bpermute_b32 v131, v148, v129
	v_cvt_pk_bf16_f32 v133, v134, v135
	v_cvt_pk_bf16_f32 v151, v138, v139
	global_store_dwordx2 v[146:147], v[132:133], off offset:256 nt
	v_cvt_pk_bf16_f32 v132, v176, v177
	s_waitcnt lgkmcnt(0)
	v_pk_add_f32 v[128:129], v[128:129], v[130:131]
	ds_bpermute_b32 v130, v149, v128
	ds_bpermute_b32 v131, v149, v129
	v_cvt_pk_bf16_f32 v133, v158, v159
	global_store_dwordx2 v[146:147], v[150:151], off offset:32 nt
	global_store_dwordx2 v[146:147], v[132:133], off offset:288 nt
	s_and_saveexec_b64 s[50:51], s[8:9]
	s_cbranch_execz .LBB0_1048
	s_waitcnt lgkmcnt(0)
	v_pk_add_f32 v[128:129], v[128:129], v[130:131]
	v_lshlrev_b64 v[130:131], 7, v[144:145]
	v_lshl_add_u64 v[130:131], s[24:25], 0, v[130:131]
	v_lshl_add_u64 v[130:131], s[14:15], 2, v[130:131]
	global_store_dwordx2 v[130:131], v[128:129], off
.LBB0_1048:
	s_or_b64 exec, exec, s[50:51]
	v_add_u32_e32 v128, s37, v187
	v_ashrrev_i32_e32 v129, 31, v128
	v_cmp_gt_i32_e32 vcc, s73, v128
	s_nop 1
	v_cndmask_b32_e32 v129, 0, v129, vcc
	s_waitcnt lgkmcnt(0)
	v_lshlrev_b64 v[130:131], 11, v[128:129]
	v_lshl_add_u64 v[130:131], s[42:43], 0, v[130:131]
	v_lshl_add_u64 v[130:131], v[174:175], 1, v[130:131]
	ds_read_b64 v[140:141], v188
	s_waitcnt vmcnt(14)
	v_lshlrev_b32_e32 v143, 16, v245
	v_and_b32_e32 v144, 0xffff0000, v245
	v_lshlrev_b32_e32 v154, 16, v247
	v_and_b32_e32 v155, 0xffff0000, v247
	v_lshlrev_b32_e32 v142, 16, v244
	v_and_b32_e32 v132, 0xffff0000, v244
	v_lshlrev_b32_e32 v152, 16, v246
	v_and_b32_e32 v153, 0xffff0000, v246
	v_lshlrev_b32_e32 v156, 16, v248
	v_and_b32_e32 v157, 0xffff0000, v248
	v_lshlrev_b32_e32 v158, 16, v249
	v_and_b32_e32 v159, 0xffff0000, v249
	s_waitcnt lgkmcnt(0)
; #define GASP __attribute__((address_space(1)))
;     __device__ __forceinline__ void operator()(Acc& acc, const Unit& u, int wr, int wc, int fr, int fq, LAS unsigned char* lds) const {
;     ...
;                 const int rl = ai * HALF + wr * 64 + m * 16 + fr, row = u.pm * BM + rl;
;                 const float* rp = (row < split) ? res0 + (size_t)row * D : res1 + (size_t)(row - split) * D;
;                 float* op = out + (size_t)row * D;
;                 f32x2 st = (f32x2){0.f, 1.f}; if (STp) st = SL[rl];
;                 float s = 0.f, q = 0.f;
; #pragma unroll
;                 for (int bj = 0; bj < 2; ++bj)
; #pragma unroll
;                     for (int n = 0; n < 2; ++n) { const int c = col0 + bj * HALF + n * 16; f32x4 r;
;                         if (resb) { const u32x2 w = *(const GASP u32x2*)(resb + (size_t)row * D + c);
;                             r = (f32x4){__uint_as_float(w.x << 16), __uint_as_float(w.x & 0xffff0000u), __uint_as_float(w.y << 16), __uint_as_float(w.y & 0xffff0000u)}; }
;                         else r = *(const GASP f32x4*)(rp + c);
;                         if (STp) r = (r - st[0]) * st[1] * gg[bj][n] + bb[bj][n];
;                         const f32x4 o = r * ALPHA + acc[ai][bj][m][n] * scale;
;                         if (out) *(GASP f32x4*)(op + c) = o;
;                         if (ob) { u32x2 w; w.x = pk2(o[0], o[1]); w.y = pk2(o[2], o[3]); *(GASP u32x2*)(ob + (size_t)row * D + c) = w; }
;                         s += (o[0] + o[1]) + (o[2] + o[3]); q += (o[0] * o[0] + o[1] * o[1]) + (o[2] * o[2] + o[3] * o[3]); }
;                 if (STn) { s += __shfl_xor(s, 16); s += __shfl_xor(s, 32); q += __shfl_xor(q, 16); q += __shfl_xor(q, 32);
;                     if (fq == 0) *(GASP f32x2*)(STn + (size_t)row * 32 + (u.pn * 4 + wc) * 2) = (f32x2){s, q}; }
	v_sub_f32_e32 v135, v144, v140
	v_sub_f32_e32 v134, v143, v140
	v_sub_f32_e32 v137, v155, v140
	v_sub_f32_e32 v136, v154, v140
	v_lshlrev_b32_e32 v165, 16, v250
	v_and_b32_e32 v176, 0xffff0000, v250
	v_lshlrev_b32_e32 v177, 16, v251
	v_and_b32_e32 v178, 0xffff0000, v251
	v_add_u32_e32 v250, s37, v191
	v_mov_b32_e32 v251, 0
	v_lshlrev_b64 v[250:251], 11, v[250:251]
	v_lshl_add_u64 v[250:251], s[42:43], 0, v[250:251]
	v_lshl_add_u64 v[250:251], v[174:175], 1, v[250:251]
	global_load_dwordx2 v[244:245], v[250:251], off
	global_load_dwordx2 v[246:247], v[250:251], off offset:32
	global_load_dwordx2 v[248:249], v[250:251], off offset:256
	global_load_dwordx2 v[250:251], v[250:251], off offset:288
	v_sub_f32_e32 v133, v132, v140
	v_sub_f32_e32 v132, v142, v140
	v_sub_f32_e32 v139, v153, v140
	v_sub_f32_e32 v138, v152, v140
	v_pk_mul_f32 v[134:135], v[140:141], v[134:135] op_sel:[1,0]
	v_pk_mul_f32 v[136:137], v[140:141], v[136:137] op_sel:[1,0]
	v_sub_f32_e32 v143, v159, v140
	v_sub_f32_e32 v142, v158, v140
	v_sub_f32_e32 v145, v157, v140
	v_sub_f32_e32 v144, v156, v140
	v_sub_f32_e32 v151, v176, v140
	v_sub_f32_e32 v150, v165, v140
	v_pk_mul_f32 v[132:133], v[140:141], v[132:133] op_sel:[1,0]
	v_pk_mul_f32 v[138:139], v[140:141], v[138:139] op_sel:[1,0]
	v_pk_fma_f32 v[134:135], v[78:79], v[134:135], v[66:67]
	v_pk_fma_f32 v[136:137], v[70:71], v[136:137], v[82:83]
	v_sub_f32_e32 v147, v178, v140
	v_sub_f32_e32 v146, v177, v140
	v_pk_mul_f32 v[144:145], v[140:141], v[144:145] op_sel:[1,0]
	v_pk_mul_f32 v[142:143], v[140:141], v[142:143] op_sel:[1,0]
	v_pk_mul_f32 v[150:151], v[140:141], v[150:151] op_sel:[1,0]
	v_pk_fma_f32 v[132:133], v[76:77], v[132:133], v[64:65]
	v_pk_fma_f32 v[138:139], v[68:69], v[138:139], v[80:81]
	v_pk_fma_f32 v[126:127], v[134:135], s[34:35], v[126:127] op_sel_hi:[1,0,1]
	v_cndmask_b32_e64 v135, v137, v155, s[10:11]
	v_cndmask_b32_e64 v134, v136, v154, s[10:11]
	v_pk_mul_f32 v[140:141], v[140:141], v[146:147] op_sel:[1,0]
	v_pk_fma_f32 v[142:143], v[74:75], v[142:143], v[86:87]
	v_pk_fma_f32 v[144:145], v[72:73], v[144:145], v[84:85]
	v_pk_fma_f32 v[146:147], v[88:89], v[150:151], v[92:93]
	v_pk_fma_f32 v[124:125], v[132:133], s[34:35], v[124:125] op_sel_hi:[1,0,1]
	v_cndmask_b32_e64 v133, v139, v153, s[10:11]
	v_cndmask_b32_e64 v132, v138, v152, s[10:11]
	v_pk_fma_f32 v[122:123], v[134:135], s[34:35], v[122:123] op_sel_hi:[1,0,1]
	v_cndmask_b32_e64 v136, v144, v156, s[10:11]
	v_cndmask_b32_e64 v138, v142, v158, s[10:11]
	v_cndmask_b32_e64 v142, v146, v165, s[10:11]
	v_cvt_pk_bf16_f32 v144, v124, v125
	v_add_f32_e32 v146, v124, v125
	v_mul_f32_e32 v153, v124, v124
	v_mul_f32_e32 v125, v125, v125
	v_pk_fma_f32 v[120:121], v[132:133], s[34:35], v[120:121] op_sel_hi:[1,0,1]
	v_mul_f32_e32 v124, v122, v122
	v_cndmask_b32_e64 v137, v145, v157, s[10:11]
	v_cvt_pk_bf16_f32 v145, v126, v127
	v_add_f32_e32 v150, v126, v127
	v_mul_f32_e32 v155, v126, v126
	v_mul_f32_e32 v127, v127, v127
	v_pk_fma_f32 v[156:157], v[122:123], v[122:123], v[124:125] op_sel_hi:[1,1,0]
	v_mov_b32_e32 v152, v120
	v_mov_b32_e32 v124, v121
	v_mov_b32_e32 v154, v122
	v_mov_b32_e32 v126, v123
	v_pk_fma_f32 v[140:141], v[90:91], v[140:141], v[94:95]
	v_cndmask_b32_e64 v139, v143, v159, s[10:11]
	v_cndmask_b32_e64 v143, v147, v176, s[10:11]
	v_cvt_pk_bf16_f32 v132, v120, v121
	v_mul_f32_e32 v147, v120, v120
	v_mul_f32_e32 v151, v121, v121
	v_pk_add_f32 v[120:121], v[152:153], v[124:125]
	v_pk_add_f32 v[124:125], v[154:155], v[126:127]
	v_pk_fma_f32 v[118:119], v[138:139], s[34:35], v[118:119] op_sel_hi:[1,0,1]
	v_pk_fma_f32 v[116:117], v[136:137], s[34:35], v[116:117] op_sel_hi:[1,0,1]
	v_cndmask_b32_e64 v141, v141, v178, s[10:11]
	v_cndmask_b32_e64 v140, v140, v177, s[10:11]
	v_pk_add_f32 v[120:121], v[120:121], v[124:125]
	v_pk_add_f32 v[124:125], v[146:147], v[150:151]
	v_mov_b32_e32 v165, v157
	global_store_dwordx2 v[130:131], v[144:145], off nt
	v_mul_f32_e32 v135, v116, v116
	v_mul_f32_e32 v137, v117, v117
	v_mul_f32_e32 v139, v118, v118
	v_mul_f32_e32 v145, v119, v119
	v_pk_fma_f32 v[140:141], v[140:141], s[34:35], v[114:115] op_sel_hi:[1,0,1]
	v_pk_fma_f32 v[142:143], v[142:143], s[34:35], v[112:113] op_sel_hi:[1,0,1]
	v_pk_add_f32 v[124:125], v[124:125], v[164:165]
	v_mov_b32_e32 v134, v116
	v_mov_b32_e32 v136, v117
	v_mov_b32_e32 v138, v118
	v_mov_b32_e32 v144, v119
	v_mul_f32_e32 v113, v142, v142
	v_mul_f32_e32 v115, v143, v143
	v_mul_f32_e32 v159, v140, v140
	v_mul_f32_e32 v177, v141, v141
	v_pk_add_f32 v[120:121], v[120:121], v[124:125]
	v_pk_add_f32 v[124:125], v[134:135], v[136:137]
	v_pk_add_f32 v[126:127], v[138:139], v[144:145]
	v_mov_b32_e32 v112, v142
	v_mov_b32_e32 v114, v143
	v_mov_b32_e32 v158, v140
	v_mov_b32_e32 v176, v141
	v_pk_add_f32 v[124:125], v[124:125], v[126:127]
	v_pk_add_f32 v[112:113], v[112:113], v[114:115]
	v_pk_add_f32 v[114:115], v[158:159], v[176:177]
	v_pk_add_f32 v[120:121], v[120:121], v[124:125]
	v_pk_add_f32 v[112:113], v[112:113], v[114:115]
	v_cvt_pk_bf16_f32 v116, v116, v117
	v_pk_add_f32 v[112:113], v[120:121], v[112:113]
	ds_bpermute_b32 v114, v148, v112
	ds_bpermute_b32 v115, v148, v113
	v_cvt_pk_bf16_f32 v117, v118, v119
	v_cvt_pk_bf16_f32 v133, v122, v123
	global_store_dwordx2 v[130:131], v[116:117], off offset:256 nt
	v_cvt_pk_bf16_f32 v116, v142, v143
	s_waitcnt lgkmcnt(0)
	v_pk_add_f32 v[112:113], v[112:113], v[114:115]
	ds_bpermute_b32 v114, v149, v112
	ds_bpermute_b32 v115, v149, v113
	v_cvt_pk_bf16_f32 v117, v140, v141
	global_store_dwordx2 v[130:131], v[132:133], off offset:32 nt
	global_store_dwordx2 v[130:131], v[116:117], off offset:288 nt
	s_and_saveexec_b64 s[50:51], s[8:9]
	s_cbranch_execz .LBB0_1050
	s_waitcnt lgkmcnt(0)
	v_pk_add_f32 v[112:113], v[112:113], v[114:115]
	v_lshlrev_b64 v[114:115], 7, v[128:129]
	v_lshl_add_u64 v[114:115], s[24:25], 0, v[114:115]
	v_lshl_add_u64 v[114:115], s[14:15], 2, v[114:115]
	global_store_dwordx2 v[114:115], v[112:113], off
; #define GASP __attribute__((address_space(1)))
;     __device__ __forceinline__ void operator()(Acc& acc, const Unit& u, int wr, int wc, int fr, int fq, LAS unsigned char* lds) const {
;     ...
;                 const int rl = ai * HALF + wr * 64 + m * 16 + fr, row = u.pm * BM + rl;
;                 const float* rp = (row < split) ? res0 + (size_t)row * D : res1 + (size_t)(row - split) * D;
;                 float* op = out + (size_t)row * D;
;                 f32x2 st = (f32x2){0.f, 1.f}; if (STp) st = SL[rl];
;                 float s = 0.f, q = 0.f;
; #pragma unroll
;                 for (int bj = 0; bj < 2; ++bj)
; #pragma unroll
;                     for (int n = 0; n < 2; ++n) { const int c = col0 + bj * HALF + n * 16; f32x4 r;
;                         if (resb) { const u32x2 w = *(const GASP u32x2*)(resb + (size_t)row * D + c);
;                             r = (f32x4){__uint_as_float(w.x << 16), __uint_as_float(w.x & 0xffff0000u), __uint_as_float(w.y << 16), __uint_as_float(w.y & 0xffff0000u)}; }
;                         else r = *(const GASP f32x4*)(rp + c);
;                         if (STp) r = (r - st[0]) * st[1] * gg[bj][n] + bb[bj][n];
;                         const f32x4 o = r * ALPHA + acc[ai][bj][m][n] * scale;
;                         if (out) *(GASP f32x4*)(op + c) = o;
;                         if (ob) { u32x2 w; w.x = pk2(o[0], o[1]); w.y = pk2(o[2], o[3]); *(GASP u32x2*)(ob + (size_t)row * D + c) = w; }
;                         s += (o[0] + o[1]) + (o[2] + o[3]); q += (o[0] * o[0] + o[1] * o[1]) + (o[2] * o[2] + o[3] * o[3]); }
;                 if (STn) { s += __shfl_xor(s, 16); s += __shfl_xor(s, 32); q += __shfl_xor(q, 16); q += __shfl_xor(q, 32);
;                     if (fq == 0) *(GASP f32x2*)(STn + (size_t)row * 32 + (u.pn * 4 + wc) * 2) = (f32x2){s, q}; }
.LBB0_1050:
	s_or_b64 exec, exec, s[50:51]
	v_add_u32_e32 v112, s37, v189
	v_ashrrev_i32_e32 v113, 31, v112
	v_cmp_gt_i32_e32 vcc, s73, v112
	s_nop 1
	v_cndmask_b32_e32 v113, 0, v113, vcc
	s_waitcnt lgkmcnt(0)
	v_lshlrev_b64 v[114:115], 11, v[112:113]
	v_lshl_add_u64 v[114:115], s[42:43], 0, v[114:115]
	v_lshl_add_u64 v[114:115], v[174:175], 1, v[114:115]
	ds_read_b64 v[124:125], v190
	s_waitcnt vmcnt(14)
	v_lshlrev_b32_e32 v127, 16, v237
	v_and_b32_e32 v128, 0xffff0000, v237
	v_lshlrev_b32_e32 v136, 16, v239
	v_and_b32_e32 v137, 0xffff0000, v239
	v_lshlrev_b32_e32 v126, 16, v236
	v_and_b32_e32 v116, 0xffff0000, v236
	v_lshlrev_b32_e32 v134, 16, v238
	v_and_b32_e32 v135, 0xffff0000, v238
	v_lshlrev_b32_e32 v138, 16, v240
	v_and_b32_e32 v139, 0xffff0000, v240
	v_lshlrev_b32_e32 v140, 16, v241
	v_and_b32_e32 v141, 0xffff0000, v241
	s_waitcnt lgkmcnt(0)
	v_sub_f32_e32 v119, v128, v124
	v_sub_f32_e32 v118, v127, v124
	v_sub_f32_e32 v121, v137, v124
	v_sub_f32_e32 v120, v136, v124
	v_lshlrev_b32_e32 v142, 16, v242
	v_and_b32_e32 v143, 0xffff0000, v242
	v_lshlrev_b32_e32 v144, 16, v243
	v_and_b32_e32 v145, 0xffff0000, v243
	v_add_u32_e32 v242, s37, v193
	v_mov_b32_e32 v243, 0
	v_lshlrev_b64 v[242:243], 11, v[242:243]
	v_lshl_add_u64 v[242:243], s[42:43], 0, v[242:243]
	v_lshl_add_u64 v[242:243], v[174:175], 1, v[242:243]
	global_load_dwordx2 v[236:237], v[242:243], off
	global_load_dwordx2 v[238:239], v[242:243], off offset:32
	global_load_dwordx2 v[240:241], v[242:243], off offset:256
	global_load_dwordx2 v[242:243], v[242:243], off offset:288
	v_sub_f32_e32 v117, v116, v124
	v_sub_f32_e32 v116, v126, v124
	v_sub_f32_e32 v123, v135, v124
	v_sub_f32_e32 v122, v134, v124
	v_pk_mul_f32 v[118:119], v[124:125], v[118:119] op_sel:[1,0]
	v_pk_mul_f32 v[120:121], v[124:125], v[120:121] op_sel:[1,0]
	v_sub_f32_e32 v127, v141, v124
	v_sub_f32_e32 v126, v140, v124
	v_sub_f32_e32 v129, v139, v124
	v_sub_f32_e32 v128, v138, v124
	v_sub_f32_e32 v133, v143, v124
	v_sub_f32_e32 v132, v142, v124
	v_pk_mul_f32 v[116:117], v[124:125], v[116:117] op_sel:[1,0]
	v_pk_mul_f32 v[122:123], v[124:125], v[122:123] op_sel:[1,0]
	v_pk_fma_f32 v[118:119], v[78:79], v[118:119], v[66:67]
	v_pk_fma_f32 v[120:121], v[70:71], v[120:121], v[82:83]
	v_sub_f32_e32 v131, v145, v124
	v_sub_f32_e32 v130, v144, v124
	v_pk_mul_f32 v[128:129], v[124:125], v[128:129] op_sel:[1,0]
	v_pk_mul_f32 v[126:127], v[124:125], v[126:127] op_sel:[1,0]
	v_pk_mul_f32 v[132:133], v[124:125], v[132:133] op_sel:[1,0]
	v_pk_fma_f32 v[116:117], v[76:77], v[116:117], v[64:65]
	v_pk_fma_f32 v[122:123], v[68:69], v[122:123], v[80:81]
	v_pk_fma_f32 v[110:111], v[118:119], s[34:35], v[110:111] op_sel_hi:[1,0,1]
	v_cndmask_b32_e64 v119, v121, v137, s[10:11]
	v_cndmask_b32_e64 v118, v120, v136, s[10:11]
	v_pk_mul_f32 v[124:125], v[124:125], v[130:131] op_sel:[1,0]
	v_pk_fma_f32 v[126:127], v[74:75], v[126:127], v[86:87]
	v_pk_fma_f32 v[128:129], v[72:73], v[128:129], v[84:85]
	v_pk_fma_f32 v[130:131], v[88:89], v[132:133], v[92:93]
	v_pk_fma_f32 v[108:109], v[116:117], s[34:35], v[108:109] op_sel_hi:[1,0,1]
	v_cndmask_b32_e64 v117, v123, v135, s[10:11]
	v_cndmask_b32_e64 v116, v122, v134, s[10:11]
	v_pk_fma_f32 v[106:107], v[118:119], s[34:35], v[106:107] op_sel_hi:[1,0,1]
	v_cndmask_b32_e64 v120, v128, v138, s[10:11]
	v_cndmask_b32_e64 v122, v126, v140, s[10:11]
	v_cndmask_b32_e64 v126, v130, v142, s[10:11]
	v_cvt_pk_bf16_f32 v128, v108, v109
	v_add_f32_e32 v130, v108, v109
	v_mul_f32_e32 v135, v108, v108
	v_mul_f32_e32 v109, v109, v109
	v_pk_fma_f32 v[104:105], v[116:117], s[34:35], v[104:105] op_sel_hi:[1,0,1]
	v_mul_f32_e32 v108, v106, v106
	v_cndmask_b32_e64 v121, v129, v139, s[10:11]
	v_cvt_pk_bf16_f32 v129, v110, v111
	v_add_f32_e32 v132, v110, v111
	v_mul_f32_e32 v137, v110, v110
	v_mul_f32_e32 v111, v111, v111
	v_pk_fma_f32 v[138:139], v[106:107], v[106:107], v[108:109] op_sel_hi:[1,1,0]
	v_mov_b32_e32 v134, v104
	v_mov_b32_e32 v108, v105
	v_mov_b32_e32 v136, v106
	v_mov_b32_e32 v110, v107
	v_pk_fma_f32 v[124:125], v[90:91], v[124:125], v[94:95]
	v_cndmask_b32_e64 v123, v127, v141, s[10:11]
	v_cndmask_b32_e64 v127, v131, v143, s[10:11]
	v_cvt_pk_bf16_f32 v116, v104, v105
	v_mul_f32_e32 v131, v104, v104
	v_mul_f32_e32 v133, v105, v105
	v_pk_add_f32 v[104:105], v[134:135], v[108:109]
	v_pk_add_f32 v[108:109], v[136:137], v[110:111]
	v_pk_fma_f32 v[102:103], v[122:123], s[34:35], v[102:103] op_sel_hi:[1,0,1]
	v_pk_fma_f32 v[100:101], v[120:121], s[34:35], v[100:101] op_sel_hi:[1,0,1]
	v_cndmask_b32_e64 v125, v125, v145, s[10:11]
	v_cndmask_b32_e64 v124, v124, v144, s[10:11]
	v_pk_add_f32 v[104:105], v[104:105], v[108:109]
	v_pk_add_f32 v[108:109], v[130:131], v[132:133]
	v_mov_b32_e32 v165, v139
	global_store_dwordx2 v[114:115], v[128:129], off nt
	v_mul_f32_e32 v119, v100, v100
	v_mul_f32_e32 v121, v101, v101
	v_mul_f32_e32 v123, v102, v102
	v_mul_f32_e32 v129, v103, v103
	v_pk_fma_f32 v[124:125], v[124:125], s[34:35], v[98:99] op_sel_hi:[1,0,1]
	v_pk_fma_f32 v[126:127], v[126:127], s[34:35], v[96:97] op_sel_hi:[1,0,1]
	v_pk_add_f32 v[108:109], v[108:109], v[164:165]
	v_mov_b32_e32 v118, v100
	v_mov_b32_e32 v120, v101
	v_mov_b32_e32 v122, v102
	v_mov_b32_e32 v128, v103
	v_mul_f32_e32 v97, v126, v126
	v_mul_f32_e32 v99, v127, v127
	v_mul_f32_e32 v141, v124, v124
	v_mul_f32_e32 v143, v125, v125
	v_pk_add_f32 v[104:105], v[104:105], v[108:109]
	v_pk_add_f32 v[108:109], v[118:119], v[120:121]
	v_pk_add_f32 v[110:111], v[122:123], v[128:129]
	v_mov_b32_e32 v96, v126
	v_mov_b32_e32 v98, v127
	v_mov_b32_e32 v140, v124
	v_mov_b32_e32 v142, v125
	v_pk_add_f32 v[108:109], v[108:109], v[110:111]
	v_pk_add_f32 v[96:97], v[96:97], v[98:99]
	v_pk_add_f32 v[98:99], v[140:141], v[142:143]
	v_pk_add_f32 v[104:105], v[104:105], v[108:109]
	v_pk_add_f32 v[96:97], v[96:97], v[98:99]
	v_cvt_pk_bf16_f32 v100, v100, v101
	v_pk_add_f32 v[96:97], v[104:105], v[96:97]
	ds_bpermute_b32 v98, v148, v96
	ds_bpermute_b32 v99, v148, v97
	v_cvt_pk_bf16_f32 v101, v102, v103
	v_cvt_pk_bf16_f32 v117, v106, v107
	global_store_dwordx2 v[114:115], v[100:101], off offset:256 nt
	v_cvt_pk_bf16_f32 v100, v126, v127
	s_waitcnt lgkmcnt(0)
	v_pk_add_f32 v[96:97], v[96:97], v[98:99]
	ds_bpermute_b32 v98, v149, v96
	ds_bpermute_b32 v99, v149, v97
	v_cvt_pk_bf16_f32 v101, v124, v125
	global_store_dwordx2 v[114:115], v[116:117], off offset:32 nt
	global_store_dwordx2 v[114:115], v[100:101], off offset:288 nt
	s_and_saveexec_b64 s[50:51], s[8:9]
	s_cbranch_execz .LBB0_1052
	s_waitcnt lgkmcnt(0)
	v_pk_add_f32 v[96:97], v[96:97], v[98:99]
	v_lshlrev_b64 v[98:99], 7, v[112:113]
	v_lshl_add_u64 v[98:99], s[24:25], 0, v[98:99]
	v_lshl_add_u64 v[98:99], s[14:15], 2, v[98:99]
	global_store_dwordx2 v[98:99], v[96:97], off
; #define GASP __attribute__((address_space(1)))
;     __device__ __forceinline__ void operator()(Acc& acc, const Unit& u, int wr, int wc, int fr, int fq, LAS unsigned char* lds) const {
;     ...
;                 const int rl = ai * HALF + wr * 64 + m * 16 + fr, row = u.pm * BM + rl;
;                 const float* rp = (row < split) ? res0 + (size_t)row * D : res1 + (size_t)(row - split) * D;
;                 float* op = out + (size_t)row * D;
;                 f32x2 st = (f32x2){0.f, 1.f}; if (STp) st = SL[rl];
;                 float s = 0.f, q = 0.f;
; #pragma unroll
;                 for (int bj = 0; bj < 2; ++bj)
; #pragma unroll
;                     for (int n = 0; n < 2; ++n) { const int c = col0 + bj * HALF + n * 16; f32x4 r;
;                         if (resb) { const u32x2 w = *(const GASP u32x2*)(resb + (size_t)row * D + c);
;                             r = (f32x4){__uint_as_float(w.x << 16), __uint_as_float(w.x & 0xffff0000u), __uint_as_float(w.y << 16), __uint_as_float(w.y & 0xffff0000u)}; }
;                         else r = *(const GASP f32x4*)(rp + c);
;                         if (STp) r = (r - st[0]) * st[1] * gg[bj][n] + bb[bj][n];
;                         const f32x4 o = r * ALPHA + acc[ai][bj][m][n] * scale;
;                         if (out) *(GASP f32x4*)(op + c) = o;
;                         if (ob) { u32x2 w; w.x = pk2(o[0], o[1]); w.y = pk2(o[2], o[3]); *(GASP u32x2*)(ob + (size_t)row * D + c) = w; }
;                         s += (o[0] + o[1]) + (o[2] + o[3]); q += (o[0] * o[0] + o[1] * o[1]) + (o[2] * o[2] + o[3] * o[3]); }
;                 if (STn) { s += __shfl_xor(s, 16); s += __shfl_xor(s, 32); q += __shfl_xor(q, 16); q += __shfl_xor(q, 32);
;                     if (fq == 0) *(GASP f32x2*)(STn + (size_t)row * 32 + (u.pn * 4 + wc) * 2) = (f32x2){s, q}; }
.LBB0_1052:
	s_or_b64 exec, exec, s[50:51]
	v_add_u32_e32 v96, s37, v191
	v_ashrrev_i32_e32 v97, 31, v96
	v_cmp_gt_i32_e32 vcc, s73, v96
	s_nop 1
	v_cndmask_b32_e32 v97, 0, v97, vcc
	s_waitcnt lgkmcnt(0)
	v_lshlrev_b64 v[98:99], 11, v[96:97]
	v_lshl_add_u64 v[98:99], s[42:43], 0, v[98:99]
	v_lshl_add_u64 v[98:99], v[174:175], 1, v[98:99]
	ds_read_b64 v[108:109], v192
	s_waitcnt vmcnt(14)
	v_lshlrev_b32_e32 v111, 16, v245
	v_and_b32_e32 v112, 0xffff0000, v245
	v_lshlrev_b32_e32 v120, 16, v247
	v_and_b32_e32 v121, 0xffff0000, v247
	v_lshlrev_b32_e32 v110, 16, v244
	v_and_b32_e32 v100, 0xffff0000, v244
	v_lshlrev_b32_e32 v118, 16, v246
	v_and_b32_e32 v119, 0xffff0000, v246
	v_lshlrev_b32_e32 v122, 16, v248
	v_and_b32_e32 v123, 0xffff0000, v248
	v_lshlrev_b32_e32 v124, 16, v249
	v_and_b32_e32 v125, 0xffff0000, v249
	s_waitcnt lgkmcnt(0)
	v_sub_f32_e32 v103, v112, v108
	v_sub_f32_e32 v102, v111, v108
	v_sub_f32_e32 v105, v121, v108
	v_sub_f32_e32 v104, v120, v108
	v_lshlrev_b32_e32 v126, 16, v250
	v_and_b32_e32 v127, 0xffff0000, v250
	v_lshlrev_b32_e32 v128, 16, v251
	v_and_b32_e32 v129, 0xffff0000, v251
	v_add_u32_e32 v250, s37, v195
	v_mov_b32_e32 v251, 0
	v_lshlrev_b64 v[250:251], 11, v[250:251]
	v_lshl_add_u64 v[250:251], s[42:43], 0, v[250:251]
	v_lshl_add_u64 v[250:251], v[174:175], 1, v[250:251]
	global_load_dwordx2 v[244:245], v[250:251], off
	global_load_dwordx2 v[246:247], v[250:251], off offset:32
	global_load_dwordx2 v[248:249], v[250:251], off offset:256
	global_load_dwordx2 v[250:251], v[250:251], off offset:288
	v_sub_f32_e32 v101, v100, v108
	v_sub_f32_e32 v100, v110, v108
	v_sub_f32_e32 v107, v119, v108
	v_sub_f32_e32 v106, v118, v108
	v_pk_mul_f32 v[102:103], v[108:109], v[102:103] op_sel:[1,0]
	v_pk_mul_f32 v[104:105], v[108:109], v[104:105] op_sel:[1,0]
	v_sub_f32_e32 v111, v125, v108
	v_sub_f32_e32 v110, v124, v108
	v_sub_f32_e32 v113, v123, v108
	v_sub_f32_e32 v112, v122, v108
	v_sub_f32_e32 v117, v127, v108
	v_sub_f32_e32 v116, v126, v108
	v_pk_mul_f32 v[100:101], v[108:109], v[100:101] op_sel:[1,0]
	v_pk_mul_f32 v[106:107], v[108:109], v[106:107] op_sel:[1,0]
	v_pk_fma_f32 v[102:103], v[78:79], v[102:103], v[66:67]
	v_pk_fma_f32 v[104:105], v[70:71], v[104:105], v[82:83]
	v_sub_f32_e32 v115, v129, v108
	v_sub_f32_e32 v114, v128, v108
	v_pk_mul_f32 v[112:113], v[108:109], v[112:113] op_sel:[1,0]
	v_pk_mul_f32 v[110:111], v[108:109], v[110:111] op_sel:[1,0]
	v_pk_mul_f32 v[116:117], v[108:109], v[116:117] op_sel:[1,0]
	v_pk_fma_f32 v[100:101], v[76:77], v[100:101], v[64:65]
	v_pk_fma_f32 v[106:107], v[68:69], v[106:107], v[80:81]
	v_pk_fma_f32 v[62:63], v[102:103], s[34:35], v[62:63] op_sel_hi:[1,0,1]
	v_cndmask_b32_e64 v103, v105, v121, s[10:11]
	v_cndmask_b32_e64 v102, v104, v120, s[10:11]
	v_pk_mul_f32 v[108:109], v[108:109], v[114:115] op_sel:[1,0]
	v_pk_fma_f32 v[110:111], v[74:75], v[110:111], v[86:87]
	v_pk_fma_f32 v[112:113], v[72:73], v[112:113], v[84:85]
	v_pk_fma_f32 v[114:115], v[88:89], v[116:117], v[92:93]
	v_pk_fma_f32 v[60:61], v[100:101], s[34:35], v[60:61] op_sel_hi:[1,0,1]
	v_cndmask_b32_e64 v101, v107, v119, s[10:11]
	v_cndmask_b32_e64 v100, v106, v118, s[10:11]
	v_pk_fma_f32 v[58:59], v[102:103], s[34:35], v[58:59] op_sel_hi:[1,0,1]
	v_cndmask_b32_e64 v104, v112, v122, s[10:11]
	v_cndmask_b32_e64 v106, v110, v124, s[10:11]
	v_cndmask_b32_e64 v110, v114, v126, s[10:11]
	v_cvt_pk_bf16_f32 v112, v60, v61
	v_add_f32_e32 v114, v60, v61
	v_mul_f32_e32 v119, v60, v60
	v_mul_f32_e32 v61, v61, v61
	v_pk_fma_f32 v[56:57], v[100:101], s[34:35], v[56:57] op_sel_hi:[1,0,1]
	v_mul_f32_e32 v60, v58, v58
	v_cndmask_b32_e64 v105, v113, v123, s[10:11]
	v_cvt_pk_bf16_f32 v113, v62, v63
	v_add_f32_e32 v116, v62, v63
	v_mul_f32_e32 v121, v62, v62
	v_mul_f32_e32 v63, v63, v63
	v_pk_fma_f32 v[122:123], v[58:59], v[58:59], v[60:61] op_sel_hi:[1,1,0]
	v_mov_b32_e32 v118, v56
	v_mov_b32_e32 v60, v57
	v_mov_b32_e32 v120, v58
	v_mov_b32_e32 v62, v59
	v_pk_fma_f32 v[108:109], v[90:91], v[108:109], v[94:95]
	v_cndmask_b32_e64 v107, v111, v125, s[10:11]
	v_cndmask_b32_e64 v111, v115, v127, s[10:11]
	v_cvt_pk_bf16_f32 v100, v56, v57
	v_mul_f32_e32 v115, v56, v56
	v_mul_f32_e32 v117, v57, v57
	v_pk_add_f32 v[56:57], v[118:119], v[60:61]
	v_pk_add_f32 v[60:61], v[120:121], v[62:63]
	v_pk_fma_f32 v[54:55], v[106:107], s[34:35], v[54:55] op_sel_hi:[1,0,1]
	v_pk_fma_f32 v[52:53], v[104:105], s[34:35], v[52:53] op_sel_hi:[1,0,1]
	v_cndmask_b32_e64 v109, v109, v129, s[10:11]
	v_cndmask_b32_e64 v108, v108, v128, s[10:11]
	v_pk_add_f32 v[56:57], v[56:57], v[60:61]
	v_pk_add_f32 v[60:61], v[114:115], v[116:117]
	v_mov_b32_e32 v165, v123
	global_store_dwordx2 v[98:99], v[112:113], off nt
	v_mul_f32_e32 v103, v52, v52
	v_mul_f32_e32 v105, v53, v53
	v_mul_f32_e32 v107, v54, v54
	v_mul_f32_e32 v113, v55, v55
	v_pk_fma_f32 v[108:109], v[108:109], s[34:35], v[50:51] op_sel_hi:[1,0,1]
	v_pk_fma_f32 v[110:111], v[110:111], s[34:35], v[48:49] op_sel_hi:[1,0,1]
	v_pk_add_f32 v[60:61], v[60:61], v[164:165]
	v_mov_b32_e32 v102, v52
	v_mov_b32_e32 v104, v53
	v_mov_b32_e32 v106, v54
	v_mov_b32_e32 v112, v55
	v_mul_f32_e32 v49, v110, v110
	v_mul_f32_e32 v51, v111, v111
	v_mul_f32_e32 v125, v108, v108
	v_mul_f32_e32 v127, v109, v109
	v_pk_add_f32 v[56:57], v[56:57], v[60:61]
	v_pk_add_f32 v[60:61], v[102:103], v[104:105]
	v_pk_add_f32 v[62:63], v[106:107], v[112:113]
	v_mov_b32_e32 v48, v110
	v_mov_b32_e32 v50, v111
	v_mov_b32_e32 v124, v108
	v_mov_b32_e32 v126, v109
	v_pk_add_f32 v[60:61], v[60:61], v[62:63]
	v_pk_add_f32 v[48:49], v[48:49], v[50:51]
	v_pk_add_f32 v[50:51], v[124:125], v[126:127]
	v_pk_add_f32 v[56:57], v[56:57], v[60:61]
	v_pk_add_f32 v[48:49], v[48:49], v[50:51]
	v_cvt_pk_bf16_f32 v52, v52, v53
	v_pk_add_f32 v[48:49], v[56:57], v[48:49]
	ds_bpermute_b32 v50, v148, v48
	ds_bpermute_b32 v51, v148, v49
	v_cvt_pk_bf16_f32 v53, v54, v55
	v_cvt_pk_bf16_f32 v101, v58, v59
	global_store_dwordx2 v[98:99], v[52:53], off offset:256 nt
	v_cvt_pk_bf16_f32 v52, v110, v111
	s_waitcnt lgkmcnt(0)
	v_pk_add_f32 v[48:49], v[48:49], v[50:51]
	ds_bpermute_b32 v50, v149, v48
	ds_bpermute_b32 v51, v149, v49
	v_cvt_pk_bf16_f32 v53, v108, v109
	global_store_dwordx2 v[98:99], v[100:101], off offset:32 nt
	global_store_dwordx2 v[98:99], v[52:53], off offset:288 nt
	s_and_saveexec_b64 s[50:51], s[8:9]
	s_cbranch_execz .LBB0_1054
	s_waitcnt lgkmcnt(0)
	v_pk_add_f32 v[48:49], v[48:49], v[50:51]
	v_lshlrev_b64 v[50:51], 7, v[96:97]
	v_lshl_add_u64 v[50:51], s[24:25], 0, v[50:51]
	v_lshl_add_u64 v[50:51], s[14:15], 2, v[50:51]
	global_store_dwordx2 v[50:51], v[48:49], off
; #define GASP __attribute__((address_space(1)))
;     __device__ __forceinline__ void operator()(Acc& acc, const Unit& u, int wr, int wc, int fr, int fq, LAS unsigned char* lds) const {
;     ...
;                 const int rl = ai * HALF + wr * 64 + m * 16 + fr, row = u.pm * BM + rl;
;                 const float* rp = (row < split) ? res0 + (size_t)row * D : res1 + (size_t)(row - split) * D;
;                 float* op = out + (size_t)row * D;
;                 f32x2 st = (f32x2){0.f, 1.f}; if (STp) st = SL[rl];
;                 float s = 0.f, q = 0.f;
; #pragma unroll
;                 for (int bj = 0; bj < 2; ++bj)
; #pragma unroll
;                     for (int n = 0; n < 2; ++n) { const int c = col0 + bj * HALF + n * 16; f32x4 r;
;                         if (resb) { const u32x2 w = *(const GASP u32x2*)(resb + (size_t)row * D + c);
;                             r = (f32x4){__uint_as_float(w.x << 16), __uint_as_float(w.x & 0xffff0000u), __uint_as_float(w.y << 16), __uint_as_float(w.y & 0xffff0000u)}; }
;                         else r = *(const GASP f32x4*)(rp + c);
;                         if (STp) r = (r - st[0]) * st[1] * gg[bj][n] + bb[bj][n];
;                         const f32x4 o = r * ALPHA + acc[ai][bj][m][n] * scale;
;                         if (out) *(GASP f32x4*)(op + c) = o;
;                         if (ob) { u32x2 w; w.x = pk2(o[0], o[1]); w.y = pk2(o[2], o[3]); *(GASP u32x2*)(ob + (size_t)row * D + c) = w; }
;                         s += (o[0] + o[1]) + (o[2] + o[3]); q += (o[0] * o[0] + o[1] * o[1]) + (o[2] * o[2] + o[3] * o[3]); }
;                 if (STn) { s += __shfl_xor(s, 16); s += __shfl_xor(s, 32); q += __shfl_xor(q, 16); q += __shfl_xor(q, 32);
;                     if (fq == 0) *(GASP f32x2*)(STn + (size_t)row * 32 + (u.pn * 4 + wc) * 2) = (f32x2){s, q}; }
.LBB0_1054:
	s_or_b64 exec, exec, s[50:51]
	v_add_u32_e32 v48, s37, v193
	v_ashrrev_i32_e32 v49, 31, v48
	v_cmp_gt_i32_e32 vcc, s73, v48
	s_nop 1
	v_cndmask_b32_e32 v49, 0, v49, vcc
	s_waitcnt lgkmcnt(0)
	v_lshlrev_b64 v[50:51], 11, v[48:49]
	v_lshl_add_u64 v[50:51], s[42:43], 0, v[50:51]
	v_lshl_add_u64 v[50:51], v[174:175], 1, v[50:51]
	ds_read_b64 v[60:61], v194
	s_waitcnt vmcnt(14)
	v_lshlrev_b32_e32 v63, 16, v237
	v_and_b32_e32 v96, 0xffff0000, v237
	v_lshlrev_b32_e32 v104, 16, v239
	v_and_b32_e32 v105, 0xffff0000, v239
	v_lshlrev_b32_e32 v62, 16, v236
	v_and_b32_e32 v52, 0xffff0000, v236
	v_lshlrev_b32_e32 v102, 16, v238
	v_and_b32_e32 v103, 0xffff0000, v238
	v_lshlrev_b32_e32 v106, 16, v240
	v_and_b32_e32 v107, 0xffff0000, v240
	v_lshlrev_b32_e32 v108, 16, v241
	v_and_b32_e32 v109, 0xffff0000, v241
	s_waitcnt lgkmcnt(0)
	v_sub_f32_e32 v55, v96, v60
	v_sub_f32_e32 v54, v63, v60
	v_sub_f32_e32 v57, v105, v60
	v_sub_f32_e32 v56, v104, v60
	v_lshlrev_b32_e32 v110, 16, v242
	v_and_b32_e32 v111, 0xffff0000, v242
	v_lshlrev_b32_e32 v112, 16, v243
	v_and_b32_e32 v113, 0xffff0000, v243
	v_add_u32_e32 v242, s37, v197
	v_mov_b32_e32 v243, 0
	v_lshlrev_b64 v[242:243], 11, v[242:243]
	v_lshl_add_u64 v[242:243], s[42:43], 0, v[242:243]
	v_lshl_add_u64 v[242:243], v[174:175], 1, v[242:243]
	global_load_dwordx2 v[236:237], v[242:243], off
	global_load_dwordx2 v[238:239], v[242:243], off offset:32
	global_load_dwordx2 v[240:241], v[242:243], off offset:256
	global_load_dwordx2 v[242:243], v[242:243], off offset:288
	v_sub_f32_e32 v53, v52, v60
	v_sub_f32_e32 v52, v62, v60
	v_sub_f32_e32 v59, v103, v60
	v_sub_f32_e32 v58, v102, v60
	v_pk_mul_f32 v[54:55], v[60:61], v[54:55] op_sel:[1,0]
	v_pk_mul_f32 v[56:57], v[60:61], v[56:57] op_sel:[1,0]
	v_sub_f32_e32 v63, v109, v60
	v_sub_f32_e32 v62, v108, v60
	v_sub_f32_e32 v97, v107, v60
	v_sub_f32_e32 v96, v106, v60
	v_sub_f32_e32 v101, v111, v60
	v_sub_f32_e32 v100, v110, v60
	v_pk_mul_f32 v[52:53], v[60:61], v[52:53] op_sel:[1,0]
	v_pk_mul_f32 v[58:59], v[60:61], v[58:59] op_sel:[1,0]
	v_pk_fma_f32 v[54:55], v[78:79], v[54:55], v[66:67]
	v_pk_fma_f32 v[56:57], v[70:71], v[56:57], v[82:83]
	v_sub_f32_e32 v99, v113, v60
	v_sub_f32_e32 v98, v112, v60
	v_pk_mul_f32 v[96:97], v[60:61], v[96:97] op_sel:[1,0]
	v_pk_mul_f32 v[62:63], v[60:61], v[62:63] op_sel:[1,0]
	v_pk_mul_f32 v[100:101], v[60:61], v[100:101] op_sel:[1,0]
	v_pk_fma_f32 v[52:53], v[76:77], v[52:53], v[64:65]
	v_pk_fma_f32 v[58:59], v[68:69], v[58:59], v[80:81]
	v_pk_fma_f32 v[46:47], v[54:55], s[34:35], v[46:47] op_sel_hi:[1,0,1]
	v_cndmask_b32_e64 v55, v57, v105, s[10:11]
	v_cndmask_b32_e64 v54, v56, v104, s[10:11]
	v_pk_mul_f32 v[60:61], v[60:61], v[98:99] op_sel:[1,0]
	v_pk_fma_f32 v[62:63], v[74:75], v[62:63], v[86:87]
	v_pk_fma_f32 v[96:97], v[72:73], v[96:97], v[84:85]
	v_pk_fma_f32 v[98:99], v[88:89], v[100:101], v[92:93]
	v_pk_fma_f32 v[44:45], v[52:53], s[34:35], v[44:45] op_sel_hi:[1,0,1]
	v_cndmask_b32_e64 v53, v59, v103, s[10:11]
	v_cndmask_b32_e64 v52, v58, v102, s[10:11]
	v_pk_fma_f32 v[42:43], v[54:55], s[34:35], v[42:43] op_sel_hi:[1,0,1]
	v_cndmask_b32_e64 v56, v96, v106, s[10:11]
	v_cndmask_b32_e64 v58, v62, v108, s[10:11]
	v_cndmask_b32_e64 v62, v98, v110, s[10:11]
	v_cvt_pk_bf16_f32 v96, v44, v45
	v_add_f32_e32 v98, v44, v45
	v_mul_f32_e32 v103, v44, v44
	v_mul_f32_e32 v45, v45, v45
	v_pk_fma_f32 v[40:41], v[52:53], s[34:35], v[40:41] op_sel_hi:[1,0,1]
	v_mul_f32_e32 v44, v42, v42
	v_cndmask_b32_e64 v57, v97, v107, s[10:11]
	v_cvt_pk_bf16_f32 v97, v46, v47
	v_add_f32_e32 v100, v46, v47
	v_mul_f32_e32 v105, v46, v46
	v_mul_f32_e32 v47, v47, v47
	v_pk_fma_f32 v[106:107], v[42:43], v[42:43], v[44:45] op_sel_hi:[1,1,0]
	v_mov_b32_e32 v102, v40
	v_mov_b32_e32 v44, v41
	v_mov_b32_e32 v104, v42
	v_mov_b32_e32 v46, v43
	v_pk_fma_f32 v[60:61], v[90:91], v[60:61], v[94:95]
	v_cndmask_b32_e64 v59, v63, v109, s[10:11]
	v_cndmask_b32_e64 v63, v99, v111, s[10:11]
	v_cvt_pk_bf16_f32 v52, v40, v41
	v_mul_f32_e32 v99, v40, v40
	v_mul_f32_e32 v101, v41, v41
	v_pk_add_f32 v[40:41], v[102:103], v[44:45]
	v_pk_add_f32 v[44:45], v[104:105], v[46:47]
	v_pk_fma_f32 v[38:39], v[58:59], s[34:35], v[38:39] op_sel_hi:[1,0,1]
	v_pk_fma_f32 v[36:37], v[56:57], s[34:35], v[36:37] op_sel_hi:[1,0,1]
	v_cndmask_b32_e64 v61, v61, v113, s[10:11]
	v_cndmask_b32_e64 v60, v60, v112, s[10:11]
	v_pk_add_f32 v[40:41], v[40:41], v[44:45]
	v_pk_add_f32 v[44:45], v[98:99], v[100:101]
	v_mov_b32_e32 v165, v107
	global_store_dwordx2 v[50:51], v[96:97], off nt
	v_mul_f32_e32 v55, v36, v36
	v_mul_f32_e32 v57, v37, v37
	v_mul_f32_e32 v59, v38, v38
	v_mul_f32_e32 v97, v39, v39
	v_pk_fma_f32 v[60:61], v[60:61], s[34:35], v[34:35] op_sel_hi:[1,0,1]
	v_pk_fma_f32 v[62:63], v[62:63], s[34:35], v[32:33] op_sel_hi:[1,0,1]
	v_pk_add_f32 v[44:45], v[44:45], v[164:165]
	v_mov_b32_e32 v54, v36
	v_mov_b32_e32 v56, v37
	v_mov_b32_e32 v58, v38
	v_mov_b32_e32 v96, v39
	v_mul_f32_e32 v33, v62, v62
	v_mul_f32_e32 v35, v63, v63
	v_mul_f32_e32 v109, v60, v60
	v_mul_f32_e32 v111, v61, v61
	v_pk_add_f32 v[40:41], v[40:41], v[44:45]
	v_pk_add_f32 v[44:45], v[54:55], v[56:57]
	v_pk_add_f32 v[46:47], v[58:59], v[96:97]
	v_mov_b32_e32 v32, v62
	v_mov_b32_e32 v34, v63
	v_mov_b32_e32 v108, v60
	v_mov_b32_e32 v110, v61
	v_pk_add_f32 v[44:45], v[44:45], v[46:47]
	v_pk_add_f32 v[32:33], v[32:33], v[34:35]
	v_pk_add_f32 v[34:35], v[108:109], v[110:111]
	v_pk_add_f32 v[40:41], v[40:41], v[44:45]
	v_pk_add_f32 v[32:33], v[32:33], v[34:35]
	v_cvt_pk_bf16_f32 v36, v36, v37
	v_pk_add_f32 v[32:33], v[40:41], v[32:33]
	ds_bpermute_b32 v34, v148, v32
	ds_bpermute_b32 v35, v148, v33
	v_cvt_pk_bf16_f32 v37, v38, v39
	v_cvt_pk_bf16_f32 v53, v42, v43
	global_store_dwordx2 v[50:51], v[36:37], off offset:256 nt
	v_cvt_pk_bf16_f32 v36, v62, v63
	s_waitcnt lgkmcnt(0)
	v_pk_add_f32 v[32:33], v[32:33], v[34:35]
	ds_bpermute_b32 v34, v149, v32
	ds_bpermute_b32 v35, v149, v33
	v_cvt_pk_bf16_f32 v37, v60, v61
	global_store_dwordx2 v[50:51], v[52:53], off offset:32 nt
	global_store_dwordx2 v[50:51], v[36:37], off offset:288 nt
	s_and_saveexec_b64 s[50:51], s[8:9]
	s_cbranch_execz .LBB0_1056
	s_waitcnt lgkmcnt(0)
	v_pk_add_f32 v[32:33], v[32:33], v[34:35]
	v_lshlrev_b64 v[34:35], 7, v[48:49]
	v_lshl_add_u64 v[34:35], s[24:25], 0, v[34:35]
	v_lshl_add_u64 v[34:35], s[14:15], 2, v[34:35]
	global_store_dwordx2 v[34:35], v[32:33], off
; #define GASP __attribute__((address_space(1)))
;     __device__ __forceinline__ void operator()(Acc& acc, const Unit& u, int wr, int wc, int fr, int fq, LAS unsigned char* lds) const {
;     ...
;                 const int rl = ai * HALF + wr * 64 + m * 16 + fr, row = u.pm * BM + rl;
;                 const float* rp = (row < split) ? res0 + (size_t)row * D : res1 + (size_t)(row - split) * D;
;                 float* op = out + (size_t)row * D;
;                 f32x2 st = (f32x2){0.f, 1.f}; if (STp) st = SL[rl];
;                 float s = 0.f, q = 0.f;
; #pragma unroll
;                 for (int bj = 0; bj < 2; ++bj)
; #pragma unroll
;                     for (int n = 0; n < 2; ++n) { const int c = col0 + bj * HALF + n * 16; f32x4 r;
;                         if (resb) { const u32x2 w = *(const GASP u32x2*)(resb + (size_t)row * D + c);
;                             r = (f32x4){__uint_as_float(w.x << 16), __uint_as_float(w.x & 0xffff0000u), __uint_as_float(w.y << 16), __uint_as_float(w.y & 0xffff0000u)}; }
;                         else r = *(const GASP f32x4*)(rp + c);
;                         if (STp) r = (r - st[0]) * st[1] * gg[bj][n] + bb[bj][n];
;                         const f32x4 o = r * ALPHA + acc[ai][bj][m][n] * scale;
;                         if (out) *(GASP f32x4*)(op + c) = o;
;                         if (ob) { u32x2 w; w.x = pk2(o[0], o[1]); w.y = pk2(o[2], o[3]); *(GASP u32x2*)(ob + (size_t)row * D + c) = w; }
;                         s += (o[0] + o[1]) + (o[2] + o[3]); q += (o[0] * o[0] + o[1] * o[1]) + (o[2] * o[2] + o[3] * o[3]); }
;                 if (STn) { s += __shfl_xor(s, 16); s += __shfl_xor(s, 32); q += __shfl_xor(q, 16); q += __shfl_xor(q, 32);
;                     if (fq == 0) *(GASP f32x2*)(STn + (size_t)row * 32 + (u.pn * 4 + wc) * 2) = (f32x2){s, q}; }
.LBB0_1056:
	s_or_b64 exec, exec, s[50:51]
	v_add_u32_e32 v32, s37, v195
	v_ashrrev_i32_e32 v33, 31, v32
	v_cmp_gt_i32_e32 vcc, s73, v32
	s_nop 1
	v_cndmask_b32_e32 v33, 0, v33, vcc
	s_waitcnt lgkmcnt(0)
	v_lshlrev_b64 v[34:35], 11, v[32:33]
	v_lshl_add_u64 v[34:35], s[42:43], 0, v[34:35]
	v_lshl_add_u64 v[34:35], v[174:175], 1, v[34:35]
	ds_read_b64 v[44:45], v196
	s_waitcnt vmcnt(14)
	v_lshlrev_b32_e32 v47, 16, v245
	v_and_b32_e32 v48, 0xffff0000, v245
	v_lshlrev_b32_e32 v56, 16, v247
	v_and_b32_e32 v57, 0xffff0000, v247
	v_lshlrev_b32_e32 v46, 16, v244
	v_and_b32_e32 v36, 0xffff0000, v244
	v_lshlrev_b32_e32 v54, 16, v246
	v_and_b32_e32 v55, 0xffff0000, v246
	v_lshlrev_b32_e32 v58, 16, v248
	v_and_b32_e32 v59, 0xffff0000, v248
	v_lshlrev_b32_e32 v60, 16, v249
	v_and_b32_e32 v61, 0xffff0000, v249
	s_waitcnt lgkmcnt(0)
	v_sub_f32_e32 v39, v48, v44
	v_sub_f32_e32 v38, v47, v44
	v_sub_f32_e32 v41, v57, v44
	v_sub_f32_e32 v40, v56, v44
	v_lshlrev_b32_e32 v62, 16, v250
	v_and_b32_e32 v63, 0xffff0000, v250
	v_lshlrev_b32_e32 v96, 16, v251
	v_and_b32_e32 v97, 0xffff0000, v251
	v_sub_f32_e32 v37, v36, v44
	v_sub_f32_e32 v36, v46, v44
	v_sub_f32_e32 v43, v55, v44
	v_sub_f32_e32 v42, v54, v44
	v_pk_mul_f32 v[38:39], v[44:45], v[38:39] op_sel:[1,0]
	v_pk_mul_f32 v[40:41], v[44:45], v[40:41] op_sel:[1,0]
	v_sub_f32_e32 v47, v61, v44
	v_sub_f32_e32 v46, v60, v44
	v_sub_f32_e32 v49, v59, v44
	v_sub_f32_e32 v48, v58, v44
	v_sub_f32_e32 v53, v63, v44
	v_sub_f32_e32 v52, v62, v44
	v_pk_mul_f32 v[36:37], v[44:45], v[36:37] op_sel:[1,0]
	v_pk_mul_f32 v[42:43], v[44:45], v[42:43] op_sel:[1,0]
	v_pk_fma_f32 v[38:39], v[78:79], v[38:39], v[66:67]
	v_pk_fma_f32 v[40:41], v[70:71], v[40:41], v[82:83]
	v_sub_f32_e32 v51, v97, v44
	v_sub_f32_e32 v50, v96, v44
	v_pk_mul_f32 v[48:49], v[44:45], v[48:49] op_sel:[1,0]
	v_pk_mul_f32 v[46:47], v[44:45], v[46:47] op_sel:[1,0]
	v_pk_mul_f32 v[52:53], v[44:45], v[52:53] op_sel:[1,0]
	v_pk_fma_f32 v[36:37], v[76:77], v[36:37], v[64:65]
	v_pk_fma_f32 v[42:43], v[68:69], v[42:43], v[80:81]
	v_pk_fma_f32 v[30:31], v[38:39], s[34:35], v[30:31] op_sel_hi:[1,0,1]
	v_cndmask_b32_e64 v39, v41, v57, s[10:11]
	v_cndmask_b32_e64 v38, v40, v56, s[10:11]
	v_pk_mul_f32 v[44:45], v[44:45], v[50:51] op_sel:[1,0]
	v_pk_fma_f32 v[46:47], v[74:75], v[46:47], v[86:87]
	v_pk_fma_f32 v[48:49], v[72:73], v[48:49], v[84:85]
	v_pk_fma_f32 v[50:51], v[88:89], v[52:53], v[92:93]
	v_pk_fma_f32 v[28:29], v[36:37], s[34:35], v[28:29] op_sel_hi:[1,0,1]
	v_cndmask_b32_e64 v37, v43, v55, s[10:11]
	v_cndmask_b32_e64 v36, v42, v54, s[10:11]
	v_pk_fma_f32 v[26:27], v[38:39], s[34:35], v[26:27] op_sel_hi:[1,0,1]
	v_cndmask_b32_e64 v40, v48, v58, s[10:11]
	v_cndmask_b32_e64 v42, v46, v60, s[10:11]
	v_cndmask_b32_e64 v46, v50, v62, s[10:11]
	v_cvt_pk_bf16_f32 v48, v28, v29
	v_add_f32_e32 v50, v28, v29
	v_mul_f32_e32 v55, v28, v28
	v_mul_f32_e32 v29, v29, v29
	v_pk_fma_f32 v[24:25], v[36:37], s[34:35], v[24:25] op_sel_hi:[1,0,1]
	v_mul_f32_e32 v28, v26, v26
	v_cndmask_b32_e64 v41, v49, v59, s[10:11]
	v_cvt_pk_bf16_f32 v49, v30, v31
	v_add_f32_e32 v52, v30, v31
	v_mul_f32_e32 v57, v30, v30
	v_mul_f32_e32 v31, v31, v31
	v_pk_fma_f32 v[58:59], v[26:27], v[26:27], v[28:29] op_sel_hi:[1,1,0]
	v_mov_b32_e32 v54, v24
	v_mov_b32_e32 v28, v25
	v_mov_b32_e32 v56, v26
	v_mov_b32_e32 v30, v27
	v_pk_fma_f32 v[44:45], v[90:91], v[44:45], v[94:95]
	v_cndmask_b32_e64 v43, v47, v61, s[10:11]
	v_cndmask_b32_e64 v47, v51, v63, s[10:11]
	v_cvt_pk_bf16_f32 v36, v24, v25
	v_mul_f32_e32 v51, v24, v24
	v_mul_f32_e32 v53, v25, v25
	v_pk_add_f32 v[24:25], v[54:55], v[28:29]
	v_pk_add_f32 v[28:29], v[56:57], v[30:31]
	v_pk_fma_f32 v[22:23], v[42:43], s[34:35], v[22:23] op_sel_hi:[1,0,1]
	v_pk_fma_f32 v[20:21], v[40:41], s[34:35], v[20:21] op_sel_hi:[1,0,1]
	v_cndmask_b32_e64 v45, v45, v97, s[10:11]
	v_cndmask_b32_e64 v44, v44, v96, s[10:11]
	v_pk_add_f32 v[24:25], v[24:25], v[28:29]
	v_pk_add_f32 v[28:29], v[50:51], v[52:53]
	v_mov_b32_e32 v165, v59
	global_store_dwordx2 v[34:35], v[48:49], off nt
	v_mul_f32_e32 v39, v20, v20
	v_mul_f32_e32 v41, v21, v21
	v_mul_f32_e32 v43, v22, v22
	v_mul_f32_e32 v49, v23, v23
	v_pk_fma_f32 v[44:45], v[44:45], s[34:35], v[18:19] op_sel_hi:[1,0,1]
	v_pk_fma_f32 v[46:47], v[46:47], s[34:35], v[16:17] op_sel_hi:[1,0,1]
	v_pk_add_f32 v[28:29], v[28:29], v[164:165]
	v_mov_b32_e32 v38, v20
	v_mov_b32_e32 v40, v21
	v_mov_b32_e32 v42, v22
	v_mov_b32_e32 v48, v23
	v_mul_f32_e32 v17, v46, v46
	v_mul_f32_e32 v19, v47, v47
	v_mul_f32_e32 v61, v44, v44
	v_mul_f32_e32 v63, v45, v45
	v_pk_add_f32 v[24:25], v[24:25], v[28:29]
	v_pk_add_f32 v[28:29], v[38:39], v[40:41]
	v_pk_add_f32 v[30:31], v[42:43], v[48:49]
	v_mov_b32_e32 v16, v46
	v_mov_b32_e32 v18, v47
	v_mov_b32_e32 v60, v44
	v_mov_b32_e32 v62, v45
	v_pk_add_f32 v[28:29], v[28:29], v[30:31]
	v_pk_add_f32 v[16:17], v[16:17], v[18:19]
	v_pk_add_f32 v[18:19], v[60:61], v[62:63]
	v_pk_add_f32 v[24:25], v[24:25], v[28:29]
	v_pk_add_f32 v[16:17], v[16:17], v[18:19]
	v_cvt_pk_bf16_f32 v20, v20, v21
	v_pk_add_f32 v[16:17], v[24:25], v[16:17]
	ds_bpermute_b32 v18, v148, v16
	ds_bpermute_b32 v19, v148, v17
	v_cvt_pk_bf16_f32 v21, v22, v23
	v_cvt_pk_bf16_f32 v37, v26, v27
	global_store_dwordx2 v[34:35], v[20:21], off offset:256 nt
	v_cvt_pk_bf16_f32 v20, v46, v47
	s_waitcnt lgkmcnt(0)
	v_pk_add_f32 v[16:17], v[16:17], v[18:19]
	ds_bpermute_b32 v18, v149, v16
	ds_bpermute_b32 v19, v149, v17
	v_cvt_pk_bf16_f32 v21, v44, v45
	global_store_dwordx2 v[34:35], v[36:37], off offset:32 nt
	global_store_dwordx2 v[34:35], v[20:21], off offset:288 nt
	s_and_saveexec_b64 s[50:51], s[8:9]
	s_cbranch_execz .LBB0_1058
	s_waitcnt lgkmcnt(0)
	v_pk_add_f32 v[16:17], v[16:17], v[18:19]
	v_lshlrev_b64 v[18:19], 7, v[32:33]
	v_lshl_add_u64 v[18:19], s[24:25], 0, v[18:19]
	v_lshl_add_u64 v[18:19], s[14:15], 2, v[18:19]
	global_store_dwordx2 v[18:19], v[16:17], off
; #define GASP __attribute__((address_space(1)))
;     __device__ __forceinline__ void operator()(Acc& acc, const Unit& u, int wr, int wc, int fr, int fq, LAS unsigned char* lds) const {
;     ...
;                 const int rl = ai * HALF + wr * 64 + m * 16 + fr, row = u.pm * BM + rl;
;                 const float* rp = (row < split) ? res0 + (size_t)row * D : res1 + (size_t)(row - split) * D;
;                 float* op = out + (size_t)row * D;
;                 f32x2 st = (f32x2){0.f, 1.f}; if (STp) st = SL[rl];
;                 float s = 0.f, q = 0.f;
; #pragma unroll
;                 for (int bj = 0; bj < 2; ++bj)
; #pragma unroll
;                     for (int n = 0; n < 2; ++n) { const int c = col0 + bj * HALF + n * 16; f32x4 r;
;                         if (resb) { const u32x2 w = *(const GASP u32x2*)(resb + (size_t)row * D + c);
;                             r = (f32x4){__uint_as_float(w.x << 16), __uint_as_float(w.x & 0xffff0000u), __uint_as_float(w.y << 16), __uint_as_float(w.y & 0xffff0000u)}; }
;                         else r = *(const GASP f32x4*)(rp + c);
;                         if (STp) r = (r - st[0]) * st[1] * gg[bj][n] + bb[bj][n];
;                         const f32x4 o = r * ALPHA + acc[ai][bj][m][n] * scale;
;                         if (out) *(GASP f32x4*)(op + c) = o;
;                         if (ob) { u32x2 w; w.x = pk2(o[0], o[1]); w.y = pk2(o[2], o[3]); *(GASP u32x2*)(ob + (size_t)row * D + c) = w; }
;                         s += (o[0] + o[1]) + (o[2] + o[3]); q += (o[0] * o[0] + o[1] * o[1]) + (o[2] * o[2] + o[3] * o[3]); }
;                 if (STn) { s += __shfl_xor(s, 16); s += __shfl_xor(s, 32); q += __shfl_xor(q, 16); q += __shfl_xor(q, 32);
;                     if (fq == 0) *(GASP f32x2*)(STn + (size_t)row * 32 + (u.pn * 4 + wc) * 2) = (f32x2){s, q}; }
.LBB0_1058:
	s_or_b64 exec, exec, s[50:51]
	v_add_u32_e32 v16, s37, v197
	v_ashrrev_i32_e32 v17, 31, v16
	v_cmp_gt_i32_e32 vcc, s73, v16
	s_nop 1
	v_cndmask_b32_e32 v17, 0, v17, vcc
	s_waitcnt lgkmcnt(0)
	v_lshlrev_b64 v[18:19], 11, v[16:17]
	v_lshl_add_u64 v[18:19], s[42:43], 0, v[18:19]
	v_lshl_add_u64 v[18:19], v[174:175], 1, v[18:19]
	ds_read_b64 v[28:29], v198
	s_waitcnt vmcnt(10)
	v_lshlrev_b32_e32 v31, 16, v237
	v_and_b32_e32 v32, 0xffff0000, v237
	v_lshlrev_b32_e32 v40, 16, v239
	v_and_b32_e32 v41, 0xffff0000, v239
	v_lshlrev_b32_e32 v30, 16, v236
	v_and_b32_e32 v20, 0xffff0000, v236
	v_lshlrev_b32_e32 v38, 16, v238
	v_and_b32_e32 v39, 0xffff0000, v238
	v_lshlrev_b32_e32 v42, 16, v240
	v_and_b32_e32 v43, 0xffff0000, v240
	v_lshlrev_b32_e32 v44, 16, v241
	v_and_b32_e32 v45, 0xffff0000, v241
	s_waitcnt lgkmcnt(0)
	v_sub_f32_e32 v23, v32, v28
	v_sub_f32_e32 v22, v31, v28
	v_sub_f32_e32 v25, v41, v28
	v_sub_f32_e32 v24, v40, v28
	v_lshlrev_b32_e32 v46, 16, v242
	v_and_b32_e32 v47, 0xffff0000, v242
	v_lshlrev_b32_e32 v48, 16, v243
	v_and_b32_e32 v49, 0xffff0000, v243
	v_sub_f32_e32 v21, v20, v28
	v_sub_f32_e32 v20, v30, v28
	v_sub_f32_e32 v27, v39, v28
	v_sub_f32_e32 v26, v38, v28
	v_pk_mul_f32 v[22:23], v[28:29], v[22:23] op_sel:[1,0]
	v_pk_mul_f32 v[24:25], v[28:29], v[24:25] op_sel:[1,0]
	v_sub_f32_e32 v31, v45, v28
	v_sub_f32_e32 v30, v44, v28
	v_sub_f32_e32 v33, v43, v28
	v_sub_f32_e32 v32, v42, v28
	v_sub_f32_e32 v37, v47, v28
	v_sub_f32_e32 v36, v46, v28
	v_pk_mul_f32 v[20:21], v[28:29], v[20:21] op_sel:[1,0]
	v_pk_mul_f32 v[26:27], v[28:29], v[26:27] op_sel:[1,0]
	v_pk_fma_f32 v[22:23], v[78:79], v[22:23], v[66:67]
	v_pk_fma_f32 v[24:25], v[70:71], v[24:25], v[82:83]
	v_sub_f32_e32 v35, v49, v28
	v_sub_f32_e32 v34, v48, v28
	v_pk_mul_f32 v[32:33], v[28:29], v[32:33] op_sel:[1,0]
	v_pk_mul_f32 v[30:31], v[28:29], v[30:31] op_sel:[1,0]
	v_pk_mul_f32 v[36:37], v[28:29], v[36:37] op_sel:[1,0]
	v_pk_fma_f32 v[20:21], v[76:77], v[20:21], v[64:65]
	v_pk_fma_f32 v[26:27], v[68:69], v[26:27], v[80:81]
	v_pk_fma_f32 v[14:15], v[22:23], s[34:35], v[14:15] op_sel_hi:[1,0,1]
	v_cndmask_b32_e64 v23, v25, v41, s[10:11]
	v_cndmask_b32_e64 v22, v24, v40, s[10:11]
	v_pk_mul_f32 v[28:29], v[28:29], v[34:35] op_sel:[1,0]
	v_pk_fma_f32 v[30:31], v[74:75], v[30:31], v[86:87]
	v_pk_fma_f32 v[32:33], v[72:73], v[32:33], v[84:85]
	v_pk_fma_f32 v[34:35], v[88:89], v[36:37], v[92:93]
	v_pk_fma_f32 v[12:13], v[20:21], s[34:35], v[12:13] op_sel_hi:[1,0,1]
	v_cndmask_b32_e64 v21, v27, v39, s[10:11]
	v_cndmask_b32_e64 v20, v26, v38, s[10:11]
	v_pk_fma_f32 v[10:11], v[22:23], s[34:35], v[10:11] op_sel_hi:[1,0,1]
	v_cndmask_b32_e64 v24, v32, v42, s[10:11]
	v_cndmask_b32_e64 v26, v30, v44, s[10:11]
	v_cndmask_b32_e64 v30, v34, v46, s[10:11]
	v_cvt_pk_bf16_f32 v32, v12, v13
	v_add_f32_e32 v34, v12, v13
	v_mul_f32_e32 v39, v12, v12
	v_mul_f32_e32 v13, v13, v13
	v_pk_fma_f32 v[8:9], v[20:21], s[34:35], v[8:9] op_sel_hi:[1,0,1]
	v_mul_f32_e32 v12, v10, v10
	v_cndmask_b32_e64 v25, v33, v43, s[10:11]
	v_cvt_pk_bf16_f32 v33, v14, v15
	v_add_f32_e32 v36, v14, v15
	v_mul_f32_e32 v41, v14, v14
	v_mul_f32_e32 v15, v15, v15
	v_pk_fma_f32 v[42:43], v[10:11], v[10:11], v[12:13] op_sel_hi:[1,1,0]
	v_mov_b32_e32 v38, v8
	v_mov_b32_e32 v12, v9
	v_mov_b32_e32 v40, v10
	v_mov_b32_e32 v14, v11
	v_pk_fma_f32 v[28:29], v[90:91], v[28:29], v[94:95]
	v_cndmask_b32_e64 v27, v31, v45, s[10:11]
	v_cndmask_b32_e64 v31, v35, v47, s[10:11]
	v_cvt_pk_bf16_f32 v20, v8, v9
	v_mul_f32_e32 v35, v8, v8
	v_mul_f32_e32 v37, v9, v9
	v_pk_add_f32 v[8:9], v[38:39], v[12:13]
	v_pk_add_f32 v[12:13], v[40:41], v[14:15]
	v_pk_fma_f32 v[6:7], v[26:27], s[34:35], v[6:7] op_sel_hi:[1,0,1]
	v_pk_fma_f32 v[4:5], v[24:25], s[34:35], v[4:5] op_sel_hi:[1,0,1]
	v_cndmask_b32_e64 v29, v29, v49, s[10:11]
	v_cndmask_b32_e64 v28, v28, v48, s[10:11]
	v_pk_add_f32 v[8:9], v[8:9], v[12:13]
	v_pk_add_f32 v[12:13], v[34:35], v[36:37]
	v_mov_b32_e32 v165, v43
	global_store_dwordx2 v[18:19], v[32:33], off nt
	v_mul_f32_e32 v23, v4, v4
	v_mul_f32_e32 v25, v5, v5
	v_mul_f32_e32 v27, v6, v6
	v_mul_f32_e32 v33, v7, v7
	v_pk_fma_f32 v[28:29], v[28:29], s[34:35], v[2:3] op_sel_hi:[1,0,1]
	v_pk_fma_f32 v[30:31], v[30:31], s[34:35], v[0:1] op_sel_hi:[1,0,1]
	v_pk_add_f32 v[12:13], v[12:13], v[164:165]
	v_mov_b32_e32 v22, v4
	v_mov_b32_e32 v24, v5
	v_mov_b32_e32 v26, v6
	v_mov_b32_e32 v32, v7
	v_mul_f32_e32 v1, v30, v30
	v_mul_f32_e32 v3, v31, v31
	v_mul_f32_e32 v45, v28, v28
	v_mul_f32_e32 v47, v29, v29
	v_pk_add_f32 v[8:9], v[8:9], v[12:13]
	v_pk_add_f32 v[12:13], v[22:23], v[24:25]
	v_pk_add_f32 v[14:15], v[26:27], v[32:33]
	v_mov_b32_e32 v0, v30
	v_mov_b32_e32 v2, v31
	v_mov_b32_e32 v44, v28
	v_mov_b32_e32 v46, v29
	v_pk_add_f32 v[12:13], v[12:13], v[14:15]
	v_pk_add_f32 v[0:1], v[0:1], v[2:3]
	v_pk_add_f32 v[2:3], v[44:45], v[46:47]
	v_pk_add_f32 v[8:9], v[8:9], v[12:13]
	v_pk_add_f32 v[0:1], v[0:1], v[2:3]
	v_cvt_pk_bf16_f32 v4, v4, v5
	v_pk_add_f32 v[0:1], v[8:9], v[0:1]
	ds_bpermute_b32 v2, v148, v0
	ds_bpermute_b32 v3, v148, v1
	v_cvt_pk_bf16_f32 v5, v6, v7
	v_cvt_pk_bf16_f32 v21, v10, v11
	global_store_dwordx2 v[18:19], v[4:5], off offset:256 nt
	v_cvt_pk_bf16_f32 v4, v30, v31
	s_waitcnt lgkmcnt(0)
	v_pk_add_f32 v[0:1], v[0:1], v[2:3]
	ds_bpermute_b32 v2, v149, v0
	ds_bpermute_b32 v3, v149, v1
	v_cvt_pk_bf16_f32 v5, v28, v29
	global_store_dwordx2 v[18:19], v[20:21], off offset:32 nt
	global_store_dwordx2 v[18:19], v[4:5], off offset:288 nt
	s_and_saveexec_b64 s[50:51], s[8:9]
	s_cbranch_execz .LBB0_1060
	s_waitcnt lgkmcnt(0)
	v_pk_add_f32 v[0:1], v[0:1], v[2:3]
	v_lshlrev_b64 v[2:3], 7, v[16:17]
	v_lshl_add_u64 v[2:3], s[24:25], 0, v[2:3]
	v_lshl_add_u64 v[2:3], s[14:15], 2, v[2:3]
	global_store_dwordx2 v[2:3], v[0:1], off
